# G2 epilogue: hoist 15 serialized x-row loads, counted vmcnt
# speedup vs baseline: 1.0014x; 1.0014x over previous
.LBB0_629:
	s_ashr_i32 s4, s3, 31
	s_lshr_b32 s4, s4, 30
	s_add_i32 s4, s3, s4
	s_and_b32 s4, s4, 0xfffffc
	s_sub_i32 s3, s3, s4
	s_lshl_b32 s4, s3, 8
	s_ashr_i32 s5, s4, 31
	v_mov_b32_e32 v50, v212
	s_lshl_b32 s12, s14, 7
	s_lshl_b64 s[16:17], s[4:5], 11
	s_add_u32 s16, s19, s16
	v_ashrrev_i32_e32 v26, 3, v50
	v_ashrrev_i32_e32 v27, 31, v26
	s_addc_u32 s17, s20, s17
	v_lshlrev_b64 v[2:3], 11, v[26:27]
	v_lshlrev_b32_e32 v6, 4, v50
	v_lshl_add_u64 v[4:5], s[16:17], 0, v[2:3]
	v_and_b32_e32 v66, 0x70, v6
	v_lshl_add_u64 v[74:75], v[4:5], 0, v[66:67]
	v_add_co_u32_e32 v78, vcc, s36, v74
	s_ashr_i32 s13, s12, 31
	s_nop 0
	v_addc_co_u32_e32 v79, vcc, 0, v75, vcc
	s_lshl_b64 s[44:45], s[12:13], 11
	v_add_co_u32_e32 v80, vcc, s37, v74
	s_add_u32 s44, s21, s44
	s_nop 0
	v_addc_co_u32_e32 v81, vcc, 0, v75, vcc
	s_addc_u32 s45, s22, s45
	v_add_co_u32_e32 v82, vcc, s38, v74
	v_lshl_add_u64 v[2:3], s[44:45], 0, v[2:3]
	s_nop 0
	v_addc_co_u32_e32 v83, vcc, 0, v75, vcc
	v_lshl_add_u64 v[76:77], v[2:3], 0, v[66:67]
	global_load_dwordx4 v[2:5], v[74:75], off
	global_load_dwordx4 v[6:9], v[78:79], off
	global_load_dwordx4 v[10:13], v[80:81], off
	global_load_dwordx4 v[14:17], v[82:83], off
	global_load_dwordx4 v[18:21], v[76:77], off
	v_add_co_u32_e32 v84, vcc, s36, v76
	v_mad_u64_u32 v[72:73], s[16:17], v26, s34, v[66:67]
	s_nop 0
	v_addc_co_u32_e32 v85, vcc, 0, v77, vcc
	global_load_dwordx4 v[22:25], v[84:85], off
	global_load_dwordx4 v[26:29], v[74:75], off offset:128
	global_load_dwordx4 v[30:33], v[78:79], off offset:128
	global_load_dwordx4 v[34:37], v[82:83], off offset:128
	global_load_dwordx4 v[98:101], v[78:79], off offset:256
	global_load_dwordx4 v[38:41], v[80:81], off offset:128
	global_load_dwordx4 v[102:105], v[80:81], off offset:256
	global_load_dwordx4 v[106:109], v[74:75], off offset:256
	global_load_dwordx4 v[42:45], v[76:77], off offset:128
	global_load_dwordx4 v[110:113], v[76:77], off offset:256
	global_load_dwordx4 v[114:117], v[82:83], off offset:256
	global_load_dwordx4 v[46:49], v[84:85], off offset:128
	global_load_dwordx4 v[118:121], v[84:85], off offset:256
	v_and_b32_e32 v68, 63, v69
	v_add_u32_e32 v97, 0x12000, v72
	s_waitcnt vmcnt(17)
	ds_write_b128 v72, v[2:5]
	s_waitcnt vmcnt(16)
	ds_write_b128 v72, v[6:9] offset:9216
	s_waitcnt vmcnt(15)
	ds_write_b128 v72, v[10:13] offset:18432
	s_waitcnt vmcnt(14)
	ds_write_b128 v72, v[14:17] offset:27648
	s_waitcnt vmcnt(13)
	ds_write_b128 v72, v[18:21] offset:36864
	s_waitcnt vmcnt(12)
	ds_write_b128 v72, v[22:25] offset:46080
	s_waitcnt lgkmcnt(0)
	s_barrier
	global_load_dwordx4 v[122:125], v[78:79], off offset:384
	global_load_dwordx4 v[126:129], v[80:81], off offset:384
	global_load_dwordx4 v[130:133], v[74:75], off offset:384
	global_load_dwordx4 v[134:137], v[76:77], off offset:384
	global_load_dwordx4 v[138:141], v[82:83], off offset:384
	global_load_dwordx4 v[142:145], v[84:85], off offset:384
	v_and_b32_e32 v2, 31, v50
	v_lshrrev_b32_e32 v3, 1, v50
	v_and_or_b32 v4, v3, s35, v2
	v_and_b32_e32 v2, 16, v3
	v_and_b32_e32 v3, 0x5f, v50
	v_mad_u32_u24 v73, v3, s34, v2
	v_add_u32_e32 v66, 0x12000, v73
	s_waitcnt vmcnt(17)
	ds_write_b128 v97, v[26:29]
	s_waitcnt vmcnt(16)
	ds_write_b128 v97, v[30:33] offset:9216
	s_waitcnt vmcnt(13)
	ds_write_b128 v97, v[38:41] offset:18432
	ds_write_b128 v97, v[34:37] offset:27648
	s_waitcnt vmcnt(10)
	ds_write_b128 v97, v[42:45] offset:36864
	s_waitcnt vmcnt(7)
	ds_write_b128 v97, v[46:49] offset:46080
	v_mad_u64_u32 v[70:71], s[16:17], v4, s34, v[2:3]
	ds_read_b128 v[2:5], v73 offset:36864
	ds_read_b128 v[146:149], v73 offset:36896
	ds_read_b128 v[6:9], v73 offset:41472
	ds_read_b128 v[150:153], v73 offset:41504
	ds_read_b128 v[10:13], v70
	ds_read_b128 v[154:157], v70 offset:32
	ds_read_b128 v[14:17], v70 offset:4608
	ds_read_b128 v[158:161], v70 offset:4640
	s_setprio 1
	s_waitcnt lgkmcnt(3)
	v_mfma_f32_32x32x16_bf16 v[50:65], v[10:13], v[2:5], 0
	v_mfma_f32_32x32x16_bf16 v[18:33], v[10:13], v[6:9], 0
	s_waitcnt lgkmcnt(1)
	v_mfma_f32_32x32x16_bf16 v[34:49], v[14:17], v[2:5], 0
	v_mfma_f32_32x32x16_bf16 v[2:17], v[14:17], v[6:9], 0
	s_setprio 0
	ds_read_b128 v[162:165], v73 offset:36928
	ds_read_b128 v[166:169], v73 offset:41536
	ds_read_b128 v[170:173], v70 offset:64
	ds_read_b128 v[174:177], v70 offset:4672
	s_setprio 1
	v_mfma_f32_32x32x16_bf16 v[50:65], v[154:157], v[146:149], v[50:65]
	s_waitcnt lgkmcnt(4)
	v_mfma_f32_32x32x16_bf16 v[2:17], v[158:161], v[150:153], v[2:17]
	v_mfma_f32_32x32x16_bf16 v[18:33], v[154:157], v[150:153], v[18:33]
	v_mfma_f32_32x32x16_bf16 v[34:49], v[158:161], v[146:149], v[34:49]
	s_setprio 0
	ds_read_b128 v[146:149], v73 offset:36960
	ds_read_b128 v[150:153], v73 offset:41568
	ds_read_b128 v[154:157], v70 offset:96
	ds_read_b128 v[158:161], v70 offset:4704
	s_setprio 1
	s_waitcnt lgkmcnt(5)
	v_mfma_f32_32x32x16_bf16 v[50:65], v[170:173], v[162:165], v[50:65]
	s_waitcnt lgkmcnt(4)
	v_mfma_f32_32x32x16_bf16 v[2:17], v[174:177], v[166:169], v[2:17]
	v_mfma_f32_32x32x16_bf16 v[18:33], v[170:173], v[166:169], v[18:33]
	v_mfma_f32_32x32x16_bf16 v[34:49], v[174:177], v[162:165], v[34:49]
	s_setprio 0
	s_setprio 1
	s_waitcnt lgkmcnt(1)
	v_mfma_f32_32x32x16_bf16 v[50:65], v[154:157], v[146:149], v[50:65]
	s_waitcnt lgkmcnt(0)
	v_mfma_f32_32x32x16_bf16 v[2:17], v[158:161], v[150:153], v[2:17]
	v_mfma_f32_32x32x16_bf16 v[18:33], v[154:157], v[150:153], v[18:33]
	v_mfma_f32_32x32x16_bf16 v[34:49], v[158:161], v[146:149], v[34:49]
	s_setprio 0
	s_barrier
	global_load_dwordx4 v[146:149], v[78:79], off offset:512
	global_load_dwordx4 v[150:153], v[80:81], off offset:512
	global_load_dwordx4 v[154:157], v[74:75], off offset:512
	global_load_dwordx4 v[158:161], v[76:77], off offset:512
	global_load_dwordx4 v[162:165], v[82:83], off offset:512
	global_load_dwordx4 v[166:169], v[84:85], off offset:512
	ds_write_b128 v72, v[106:109]
	ds_write_b128 v72, v[98:101] offset:9216
	ds_write_b128 v72, v[102:105] offset:18432
	ds_write_b128 v72, v[114:117] offset:27648
	ds_write_b128 v72, v[110:113] offset:36864
	s_waitcnt vmcnt(12)
	ds_write_b128 v72, v[118:121] offset:46080
	v_add_u32_e32 v71, 0x12000, v70
	ds_read_b128 v[98:101], v66 offset:36864
	ds_read_b128 v[102:105], v66 offset:36896
	ds_read_b128 v[106:109], v66 offset:41472
	ds_read_b128 v[110:113], v66 offset:41504
	ds_read_b128 v[114:117], v71
	ds_read_b128 v[118:121], v71 offset:32
	ds_read_b128 v[170:173], v71 offset:4608
	ds_read_b128 v[174:177], v71 offset:4640
	s_setprio 1
	s_waitcnt lgkmcnt(3)
	v_mfma_f32_32x32x16_bf16 v[50:65], v[114:117], v[98:101], v[50:65]
	s_waitcnt lgkmcnt(1)
	v_mfma_f32_32x32x16_bf16 v[2:17], v[170:173], v[106:109], v[2:17]
	v_mfma_f32_32x32x16_bf16 v[18:33], v[114:117], v[106:109], v[18:33]
	v_mfma_f32_32x32x16_bf16 v[34:49], v[170:173], v[98:101], v[34:49]
	s_setprio 0
	ds_read_b128 v[98:101], v66 offset:36928
	ds_read_b128 v[106:109], v66 offset:41536
	ds_read_b128 v[114:117], v71 offset:64
	ds_read_b128 v[170:173], v71 offset:4672
	s_setprio 1
	v_mfma_f32_32x32x16_bf16 v[50:65], v[118:121], v[102:105], v[50:65]
	s_waitcnt lgkmcnt(4)
	v_mfma_f32_32x32x16_bf16 v[2:17], v[174:177], v[110:113], v[2:17]
	v_mfma_f32_32x32x16_bf16 v[18:33], v[118:121], v[110:113], v[18:33]
	v_mfma_f32_32x32x16_bf16 v[34:49], v[174:177], v[102:105], v[34:49]
	s_setprio 0
	ds_read_b128 v[102:105], v66 offset:36960
	ds_read_b128 v[110:113], v66 offset:41568
	ds_read_b128 v[118:121], v71 offset:96
	ds_read_b128 v[174:177], v71 offset:4704
	s_setprio 1
	s_waitcnt lgkmcnt(5)
	v_mfma_f32_32x32x16_bf16 v[50:65], v[114:117], v[98:101], v[50:65]
	s_waitcnt lgkmcnt(4)
	v_mfma_f32_32x32x16_bf16 v[2:17], v[170:173], v[106:109], v[2:17]
	v_mfma_f32_32x32x16_bf16 v[18:33], v[114:117], v[106:109], v[18:33]
	v_mfma_f32_32x32x16_bf16 v[34:49], v[170:173], v[98:101], v[34:49]
	s_setprio 0
	s_setprio 1
	s_waitcnt lgkmcnt(1)
	v_mfma_f32_32x32x16_bf16 v[50:65], v[118:121], v[102:105], v[50:65]
	s_waitcnt lgkmcnt(0)
	v_mfma_f32_32x32x16_bf16 v[2:17], v[174:177], v[110:113], v[2:17]
	v_mfma_f32_32x32x16_bf16 v[18:33], v[118:121], v[110:113], v[18:33]
	v_mfma_f32_32x32x16_bf16 v[34:49], v[174:177], v[102:105], v[34:49]
	s_setprio 0
	s_barrier
	global_load_dwordx4 v[98:101], v[78:79], off offset:640
	global_load_dwordx4 v[102:105], v[80:81], off offset:640
	global_load_dwordx4 v[106:109], v[74:75], off offset:640
	global_load_dwordx4 v[110:113], v[76:77], off offset:640
	global_load_dwordx4 v[114:117], v[82:83], off offset:640
	global_load_dwordx4 v[118:121], v[84:85], off offset:640
	s_waitcnt vmcnt(15)
	ds_write_b128 v97, v[130:133]
	ds_write_b128 v97, v[122:125] offset:9216
	ds_write_b128 v97, v[126:129] offset:18432
	s_waitcnt vmcnt(13)
	ds_write_b128 v97, v[138:141] offset:27648
	ds_write_b128 v97, v[134:137] offset:36864
	s_waitcnt vmcnt(12)
	ds_write_b128 v97, v[142:145] offset:46080
	ds_read_b128 v[122:125], v73 offset:36864
	ds_read_b128 v[126:129], v73 offset:36896
	ds_read_b128 v[130:133], v73 offset:41472
	ds_read_b128 v[134:137], v73 offset:41504
	ds_read_b128 v[138:141], v70
	ds_read_b128 v[142:145], v70 offset:32
	ds_read_b128 v[170:173], v70 offset:4608
	ds_read_b128 v[174:177], v70 offset:4640
	s_setprio 1
	s_waitcnt lgkmcnt(3)
	v_mfma_f32_32x32x16_bf16 v[50:65], v[138:141], v[122:125], v[50:65]
	s_waitcnt lgkmcnt(1)
	v_mfma_f32_32x32x16_bf16 v[2:17], v[170:173], v[130:133], v[2:17]
	v_mfma_f32_32x32x16_bf16 v[18:33], v[138:141], v[130:133], v[18:33]
	v_mfma_f32_32x32x16_bf16 v[34:49], v[170:173], v[122:125], v[34:49]
	s_setprio 0
	ds_read_b128 v[122:125], v73 offset:36928
	ds_read_b128 v[130:133], v73 offset:41536
	ds_read_b128 v[138:141], v70 offset:64
	ds_read_b128 v[170:173], v70 offset:4672
	s_setprio 1
	v_mfma_f32_32x32x16_bf16 v[50:65], v[142:145], v[126:129], v[50:65]
	s_waitcnt lgkmcnt(4)
	v_mfma_f32_32x32x16_bf16 v[2:17], v[174:177], v[134:137], v[2:17]
	v_mfma_f32_32x32x16_bf16 v[18:33], v[142:145], v[134:137], v[18:33]
	v_mfma_f32_32x32x16_bf16 v[34:49], v[174:177], v[126:129], v[34:49]
	s_setprio 0
	ds_read_b128 v[126:129], v73 offset:36960
	ds_read_b128 v[134:137], v73 offset:41568
	ds_read_b128 v[142:145], v70 offset:96
	ds_read_b128 v[174:177], v70 offset:4704
	s_setprio 1
	s_waitcnt lgkmcnt(5)
	v_mfma_f32_32x32x16_bf16 v[50:65], v[138:141], v[122:125], v[50:65]
	s_waitcnt lgkmcnt(4)
	v_mfma_f32_32x32x16_bf16 v[2:17], v[170:173], v[130:133], v[2:17]
	v_mfma_f32_32x32x16_bf16 v[18:33], v[138:141], v[130:133], v[18:33]
	v_mfma_f32_32x32x16_bf16 v[34:49], v[170:173], v[122:125], v[34:49]
	s_setprio 0
	s_setprio 1
	s_waitcnt lgkmcnt(1)
	v_mfma_f32_32x32x16_bf16 v[50:65], v[142:145], v[126:129], v[50:65]
	s_waitcnt lgkmcnt(0)
	v_mfma_f32_32x32x16_bf16 v[2:17], v[174:177], v[134:137], v[2:17]
	v_mfma_f32_32x32x16_bf16 v[18:33], v[142:145], v[134:137], v[18:33]
	v_mfma_f32_32x32x16_bf16 v[34:49], v[174:177], v[126:129], v[34:49]
	s_setprio 0
	s_barrier
	global_load_dwordx4 v[122:125], v[78:79], off offset:768
	global_load_dwordx4 v[126:129], v[80:81], off offset:768
	global_load_dwordx4 v[130:133], v[74:75], off offset:768
	global_load_dwordx4 v[134:137], v[76:77], off offset:768
	global_load_dwordx4 v[138:141], v[82:83], off offset:768
	global_load_dwordx4 v[142:145], v[84:85], off offset:768
	s_waitcnt vmcnt(15)
	ds_write_b128 v72, v[154:157]
	ds_write_b128 v72, v[146:149] offset:9216
	ds_write_b128 v72, v[150:153] offset:18432
	s_waitcnt vmcnt(13)
	ds_write_b128 v72, v[162:165] offset:27648
	ds_write_b128 v72, v[158:161] offset:36864
	s_waitcnt vmcnt(12)
	ds_write_b128 v72, v[166:169] offset:46080
	ds_read_b128 v[146:149], v66 offset:36864
	ds_read_b128 v[150:153], v66 offset:36896
	ds_read_b128 v[154:157], v66 offset:41472
	ds_read_b128 v[158:161], v66 offset:41504
	ds_read_b128 v[162:165], v71
	ds_read_b128 v[166:169], v71 offset:32
	ds_read_b128 v[170:173], v71 offset:4608
	ds_read_b128 v[174:177], v71 offset:4640
	s_setprio 1
	s_waitcnt lgkmcnt(3)
	v_mfma_f32_32x32x16_bf16 v[50:65], v[162:165], v[146:149], v[50:65]
	s_waitcnt lgkmcnt(1)
	v_mfma_f32_32x32x16_bf16 v[2:17], v[170:173], v[154:157], v[2:17]
	v_mfma_f32_32x32x16_bf16 v[18:33], v[162:165], v[154:157], v[18:33]
	v_mfma_f32_32x32x16_bf16 v[34:49], v[170:173], v[146:149], v[34:49]
	s_setprio 0
	ds_read_b128 v[146:149], v66 offset:36928
	ds_read_b128 v[154:157], v66 offset:41536
	ds_read_b128 v[162:165], v71 offset:64
	ds_read_b128 v[170:173], v71 offset:4672
	s_setprio 1
	v_mfma_f32_32x32x16_bf16 v[50:65], v[166:169], v[150:153], v[50:65]
	s_waitcnt lgkmcnt(4)
	v_mfma_f32_32x32x16_bf16 v[2:17], v[174:177], v[158:161], v[2:17]
	v_mfma_f32_32x32x16_bf16 v[18:33], v[166:169], v[158:161], v[18:33]
	v_mfma_f32_32x32x16_bf16 v[34:49], v[174:177], v[150:153], v[34:49]
	s_setprio 0
	ds_read_b128 v[150:153], v66 offset:36960
	ds_read_b128 v[158:161], v66 offset:41568
	ds_read_b128 v[166:169], v71 offset:96
	ds_read_b128 v[174:177], v71 offset:4704
	s_setprio 1
	s_waitcnt lgkmcnt(5)
	v_mfma_f32_32x32x16_bf16 v[50:65], v[162:165], v[146:149], v[50:65]
	s_waitcnt lgkmcnt(4)
	v_mfma_f32_32x32x16_bf16 v[2:17], v[170:173], v[154:157], v[2:17]
	v_mfma_f32_32x32x16_bf16 v[18:33], v[162:165], v[154:157], v[18:33]
	v_mfma_f32_32x32x16_bf16 v[34:49], v[170:173], v[146:149], v[34:49]
	s_setprio 0
	s_setprio 1
	s_waitcnt lgkmcnt(1)
	v_mfma_f32_32x32x16_bf16 v[50:65], v[166:169], v[150:153], v[50:65]
	s_waitcnt lgkmcnt(0)
	v_mfma_f32_32x32x16_bf16 v[2:17], v[174:177], v[158:161], v[2:17]
	v_mfma_f32_32x32x16_bf16 v[18:33], v[166:169], v[158:161], v[18:33]
	v_mfma_f32_32x32x16_bf16 v[34:49], v[174:177], v[150:153], v[34:49]
	s_setprio 0
	s_barrier
	global_load_dwordx4 v[146:149], v[78:79], off offset:896
	global_load_dwordx4 v[150:153], v[80:81], off offset:896
	global_load_dwordx4 v[154:157], v[74:75], off offset:896
	global_load_dwordx4 v[158:161], v[76:77], off offset:896
	global_load_dwordx4 v[162:165], v[82:83], off offset:896
	global_load_dwordx4 v[166:169], v[84:85], off offset:896
	s_waitcnt vmcnt(15)
	ds_write_b128 v97, v[106:109]
	ds_write_b128 v97, v[98:101] offset:9216
	ds_write_b128 v97, v[102:105] offset:18432
	s_waitcnt vmcnt(13)
	ds_write_b128 v97, v[114:117] offset:27648
	ds_write_b128 v97, v[110:113] offset:36864
	s_waitcnt vmcnt(12)
	ds_write_b128 v97, v[118:121] offset:46080
	ds_read_b128 v[98:101], v73 offset:36864
	ds_read_b128 v[102:105], v73 offset:36896
	ds_read_b128 v[106:109], v73 offset:41472
	ds_read_b128 v[110:113], v73 offset:41504
	ds_read_b128 v[114:117], v70
	ds_read_b128 v[118:121], v70 offset:32
	ds_read_b128 v[170:173], v70 offset:4608
	ds_read_b128 v[174:177], v70 offset:4640
	s_setprio 1
	s_waitcnt lgkmcnt(3)
	v_mfma_f32_32x32x16_bf16 v[50:65], v[114:117], v[98:101], v[50:65]
	s_waitcnt lgkmcnt(1)
	v_mfma_f32_32x32x16_bf16 v[2:17], v[170:173], v[106:109], v[2:17]
	v_mfma_f32_32x32x16_bf16 v[18:33], v[114:117], v[106:109], v[18:33]
	v_mfma_f32_32x32x16_bf16 v[34:49], v[170:173], v[98:101], v[34:49]
	s_setprio 0
	ds_read_b128 v[98:101], v73 offset:36928
	ds_read_b128 v[106:109], v73 offset:41536
	ds_read_b128 v[114:117], v70 offset:64
	ds_read_b128 v[170:173], v70 offset:4672
	s_setprio 1
	v_mfma_f32_32x32x16_bf16 v[50:65], v[118:121], v[102:105], v[50:65]
	s_waitcnt lgkmcnt(4)
	v_mfma_f32_32x32x16_bf16 v[2:17], v[174:177], v[110:113], v[2:17]
	v_mfma_f32_32x32x16_bf16 v[18:33], v[118:121], v[110:113], v[18:33]
	v_mfma_f32_32x32x16_bf16 v[34:49], v[174:177], v[102:105], v[34:49]
	s_setprio 0
	ds_read_b128 v[102:105], v73 offset:36960
	ds_read_b128 v[110:113], v73 offset:41568
	ds_read_b128 v[118:121], v70 offset:96
	ds_read_b128 v[174:177], v70 offset:4704
	s_setprio 1
	s_waitcnt lgkmcnt(5)
	v_mfma_f32_32x32x16_bf16 v[50:65], v[114:117], v[98:101], v[50:65]
	s_waitcnt lgkmcnt(4)
	v_mfma_f32_32x32x16_bf16 v[2:17], v[170:173], v[106:109], v[2:17]
	v_mfma_f32_32x32x16_bf16 v[18:33], v[114:117], v[106:109], v[18:33]
	v_mfma_f32_32x32x16_bf16 v[34:49], v[170:173], v[98:101], v[34:49]
	s_setprio 0
	s_setprio 1
	s_waitcnt lgkmcnt(1)
	v_mfma_f32_32x32x16_bf16 v[50:65], v[118:121], v[102:105], v[50:65]
	s_waitcnt lgkmcnt(0)
	v_mfma_f32_32x32x16_bf16 v[2:17], v[174:177], v[110:113], v[2:17]
	v_mfma_f32_32x32x16_bf16 v[18:33], v[118:121], v[110:113], v[18:33]
	v_mfma_f32_32x32x16_bf16 v[34:49], v[174:177], v[102:105], v[34:49]
	s_setprio 0
	s_barrier
	global_load_dwordx4 v[98:101], v[78:79], off offset:1024
	global_load_dwordx4 v[102:105], v[80:81], off offset:1024
	global_load_dwordx4 v[106:109], v[74:75], off offset:1024
	global_load_dwordx4 v[110:113], v[76:77], off offset:1024
	global_load_dwordx4 v[114:117], v[82:83], off offset:1024
	global_load_dwordx4 v[118:121], v[84:85], off offset:1024
	s_waitcnt vmcnt(15)
	ds_write_b128 v72, v[130:133]
	ds_write_b128 v72, v[122:125] offset:9216
	ds_write_b128 v72, v[126:129] offset:18432
	s_waitcnt vmcnt(13)
	ds_write_b128 v72, v[138:141] offset:27648
	ds_write_b128 v72, v[134:137] offset:36864
	s_waitcnt vmcnt(12)
	ds_write_b128 v72, v[142:145] offset:46080
	ds_read_b128 v[122:125], v66 offset:36864
	ds_read_b128 v[126:129], v66 offset:36896
	ds_read_b128 v[130:133], v66 offset:41472
	ds_read_b128 v[134:137], v66 offset:41504
	ds_read_b128 v[138:141], v71
	ds_read_b128 v[142:145], v71 offset:32
	ds_read_b128 v[170:173], v71 offset:4608
	ds_read_b128 v[174:177], v71 offset:4640
	s_setprio 1
	s_waitcnt lgkmcnt(3)
	v_mfma_f32_32x32x16_bf16 v[50:65], v[138:141], v[122:125], v[50:65]
	s_waitcnt lgkmcnt(1)
	v_mfma_f32_32x32x16_bf16 v[2:17], v[170:173], v[130:133], v[2:17]
	v_mfma_f32_32x32x16_bf16 v[18:33], v[138:141], v[130:133], v[18:33]
	v_mfma_f32_32x32x16_bf16 v[34:49], v[170:173], v[122:125], v[34:49]
	s_setprio 0
	ds_read_b128 v[122:125], v66 offset:36928
	ds_read_b128 v[130:133], v66 offset:41536
	ds_read_b128 v[138:141], v71 offset:64
	ds_read_b128 v[170:173], v71 offset:4672
	s_setprio 1
	v_mfma_f32_32x32x16_bf16 v[50:65], v[142:145], v[126:129], v[50:65]
	s_waitcnt lgkmcnt(4)
	v_mfma_f32_32x32x16_bf16 v[2:17], v[174:177], v[134:137], v[2:17]
	v_mfma_f32_32x32x16_bf16 v[18:33], v[142:145], v[134:137], v[18:33]
	v_mfma_f32_32x32x16_bf16 v[34:49], v[174:177], v[126:129], v[34:49]
	s_setprio 0
	ds_read_b128 v[126:129], v66 offset:36960
	ds_read_b128 v[134:137], v66 offset:41568
	ds_read_b128 v[142:145], v71 offset:96
	ds_read_b128 v[174:177], v71 offset:4704
	s_setprio 1
	s_waitcnt lgkmcnt(5)
	v_mfma_f32_32x32x16_bf16 v[50:65], v[138:141], v[122:125], v[50:65]
	s_waitcnt lgkmcnt(4)
	v_mfma_f32_32x32x16_bf16 v[2:17], v[170:173], v[130:133], v[2:17]
	v_mfma_f32_32x32x16_bf16 v[18:33], v[138:141], v[130:133], v[18:33]
	v_mfma_f32_32x32x16_bf16 v[34:49], v[170:173], v[122:125], v[34:49]
	s_setprio 0
	s_setprio 1
	s_waitcnt lgkmcnt(1)
	v_mfma_f32_32x32x16_bf16 v[50:65], v[142:145], v[126:129], v[50:65]
	s_waitcnt lgkmcnt(0)
	v_mfma_f32_32x32x16_bf16 v[2:17], v[174:177], v[134:137], v[2:17]
	v_mfma_f32_32x32x16_bf16 v[18:33], v[142:145], v[134:137], v[18:33]
	v_mfma_f32_32x32x16_bf16 v[34:49], v[174:177], v[126:129], v[34:49]
	s_setprio 0
	s_barrier
	global_load_dwordx4 v[122:125], v[78:79], off offset:1152
	global_load_dwordx4 v[126:129], v[80:81], off offset:1152
	global_load_dwordx4 v[130:133], v[74:75], off offset:1152
	global_load_dwordx4 v[134:137], v[76:77], off offset:1152
	global_load_dwordx4 v[138:141], v[82:83], off offset:1152
	global_load_dwordx4 v[142:145], v[84:85], off offset:1152
	s_waitcnt vmcnt(15)
	ds_write_b128 v97, v[154:157]
	ds_write_b128 v97, v[146:149] offset:9216
	ds_write_b128 v97, v[150:153] offset:18432
	s_waitcnt vmcnt(13)
	ds_write_b128 v97, v[162:165] offset:27648
	ds_write_b128 v97, v[158:161] offset:36864
	s_waitcnt vmcnt(12)
	ds_write_b128 v97, v[166:169] offset:46080
	ds_read_b128 v[146:149], v73 offset:36864
	ds_read_b128 v[150:153], v73 offset:36896
	ds_read_b128 v[154:157], v73 offset:41472
	ds_read_b128 v[158:161], v73 offset:41504
	ds_read_b128 v[162:165], v70
	ds_read_b128 v[166:169], v70 offset:32
	ds_read_b128 v[170:173], v70 offset:4608
	ds_read_b128 v[174:177], v70 offset:4640
	s_setprio 1
	s_waitcnt lgkmcnt(3)
	v_mfma_f32_32x32x16_bf16 v[50:65], v[162:165], v[146:149], v[50:65]
	s_waitcnt lgkmcnt(1)
	v_mfma_f32_32x32x16_bf16 v[2:17], v[170:173], v[154:157], v[2:17]
	v_mfma_f32_32x32x16_bf16 v[18:33], v[162:165], v[154:157], v[18:33]
	v_mfma_f32_32x32x16_bf16 v[34:49], v[170:173], v[146:149], v[34:49]
	s_setprio 0
	ds_read_b128 v[146:149], v73 offset:36928
	ds_read_b128 v[154:157], v73 offset:41536
	ds_read_b128 v[162:165], v70 offset:64
	ds_read_b128 v[170:173], v70 offset:4672
	s_setprio 1
	v_mfma_f32_32x32x16_bf16 v[50:65], v[166:169], v[150:153], v[50:65]
	s_waitcnt lgkmcnt(4)
	v_mfma_f32_32x32x16_bf16 v[2:17], v[174:177], v[158:161], v[2:17]
	v_mfma_f32_32x32x16_bf16 v[18:33], v[166:169], v[158:161], v[18:33]
	v_mfma_f32_32x32x16_bf16 v[34:49], v[174:177], v[150:153], v[34:49]
	s_setprio 0
	ds_read_b128 v[150:153], v73 offset:36960
	ds_read_b128 v[158:161], v73 offset:41568
	ds_read_b128 v[166:169], v70 offset:96
	ds_read_b128 v[174:177], v70 offset:4704
	s_setprio 1
	s_waitcnt lgkmcnt(5)
	v_mfma_f32_32x32x16_bf16 v[50:65], v[162:165], v[146:149], v[50:65]
	s_waitcnt lgkmcnt(4)
	v_mfma_f32_32x32x16_bf16 v[2:17], v[170:173], v[154:157], v[2:17]
	v_mfma_f32_32x32x16_bf16 v[18:33], v[162:165], v[154:157], v[18:33]
	v_mfma_f32_32x32x16_bf16 v[34:49], v[170:173], v[146:149], v[34:49]
	s_setprio 0
	s_setprio 1
	s_waitcnt lgkmcnt(1)
	v_mfma_f32_32x32x16_bf16 v[50:65], v[166:169], v[150:153], v[50:65]
	s_waitcnt lgkmcnt(0)
	v_mfma_f32_32x32x16_bf16 v[2:17], v[174:177], v[158:161], v[2:17]
	v_mfma_f32_32x32x16_bf16 v[18:33], v[166:169], v[158:161], v[18:33]
	v_mfma_f32_32x32x16_bf16 v[34:49], v[174:177], v[150:153], v[34:49]
	s_setprio 0
	s_barrier
	global_load_dwordx4 v[146:149], v[78:79], off offset:1280
	global_load_dwordx4 v[150:153], v[80:81], off offset:1280
	global_load_dwordx4 v[154:157], v[74:75], off offset:1280
	global_load_dwordx4 v[158:161], v[76:77], off offset:1280
	global_load_dwordx4 v[162:165], v[82:83], off offset:1280
	global_load_dwordx4 v[166:169], v[84:85], off offset:1280
	s_waitcnt vmcnt(15)
	ds_write_b128 v72, v[106:109]
	ds_write_b128 v72, v[98:101] offset:9216
	ds_write_b128 v72, v[102:105] offset:18432
	s_waitcnt vmcnt(13)
	ds_write_b128 v72, v[114:117] offset:27648
	ds_write_b128 v72, v[110:113] offset:36864
	s_waitcnt vmcnt(12)
	ds_write_b128 v72, v[118:121] offset:46080
	ds_read_b128 v[98:101], v66 offset:36864
	ds_read_b128 v[102:105], v66 offset:36896
	ds_read_b128 v[106:109], v66 offset:41472
	ds_read_b128 v[110:113], v66 offset:41504
	ds_read_b128 v[114:117], v71
	ds_read_b128 v[118:121], v71 offset:32
	ds_read_b128 v[170:173], v71 offset:4608
	ds_read_b128 v[174:177], v71 offset:4640
	s_setprio 1
	s_waitcnt lgkmcnt(3)
	v_mfma_f32_32x32x16_bf16 v[50:65], v[114:117], v[98:101], v[50:65]
	s_waitcnt lgkmcnt(1)
	v_mfma_f32_32x32x16_bf16 v[2:17], v[170:173], v[106:109], v[2:17]
	v_mfma_f32_32x32x16_bf16 v[18:33], v[114:117], v[106:109], v[18:33]
	v_mfma_f32_32x32x16_bf16 v[34:49], v[170:173], v[98:101], v[34:49]
	s_setprio 0
	ds_read_b128 v[98:101], v66 offset:36928
	ds_read_b128 v[106:109], v66 offset:41536
	ds_read_b128 v[114:117], v71 offset:64
	ds_read_b128 v[170:173], v71 offset:4672
	s_setprio 1
	v_mfma_f32_32x32x16_bf16 v[50:65], v[118:121], v[102:105], v[50:65]
	s_waitcnt lgkmcnt(4)
	v_mfma_f32_32x32x16_bf16 v[2:17], v[174:177], v[110:113], v[2:17]
	v_mfma_f32_32x32x16_bf16 v[18:33], v[118:121], v[110:113], v[18:33]
	v_mfma_f32_32x32x16_bf16 v[34:49], v[174:177], v[102:105], v[34:49]
	s_setprio 0
	ds_read_b128 v[102:105], v66 offset:36960
	ds_read_b128 v[110:113], v66 offset:41568
	ds_read_b128 v[118:121], v71 offset:96
	ds_read_b128 v[174:177], v71 offset:4704
	s_setprio 1
	s_waitcnt lgkmcnt(5)
	v_mfma_f32_32x32x16_bf16 v[50:65], v[114:117], v[98:101], v[50:65]
	s_waitcnt lgkmcnt(4)
	v_mfma_f32_32x32x16_bf16 v[2:17], v[170:173], v[106:109], v[2:17]
	v_mfma_f32_32x32x16_bf16 v[18:33], v[114:117], v[106:109], v[18:33]
	v_mfma_f32_32x32x16_bf16 v[34:49], v[170:173], v[98:101], v[34:49]
	s_setprio 0
	s_setprio 1
	s_waitcnt lgkmcnt(1)
	v_mfma_f32_32x32x16_bf16 v[50:65], v[118:121], v[102:105], v[50:65]
	s_waitcnt lgkmcnt(0)
	v_mfma_f32_32x32x16_bf16 v[2:17], v[174:177], v[110:113], v[2:17]
	v_mfma_f32_32x32x16_bf16 v[18:33], v[118:121], v[110:113], v[18:33]
	v_mfma_f32_32x32x16_bf16 v[34:49], v[174:177], v[102:105], v[34:49]
	s_setprio 0
	s_barrier
	global_load_dwordx4 v[98:101], v[78:79], off offset:1408
	global_load_dwordx4 v[102:105], v[80:81], off offset:1408
	global_load_dwordx4 v[106:109], v[74:75], off offset:1408
	global_load_dwordx4 v[110:113], v[76:77], off offset:1408
	global_load_dwordx4 v[114:117], v[82:83], off offset:1408
	global_load_dwordx4 v[118:121], v[84:85], off offset:1408
	s_waitcnt vmcnt(15)
	ds_write_b128 v97, v[130:133]
	ds_write_b128 v97, v[122:125] offset:9216
	ds_write_b128 v97, v[126:129] offset:18432
	s_waitcnt vmcnt(13)
	ds_write_b128 v97, v[138:141] offset:27648
	ds_write_b128 v97, v[134:137] offset:36864
	s_waitcnt vmcnt(12)
	ds_write_b128 v97, v[142:145] offset:46080
	ds_read_b128 v[122:125], v73 offset:36864
	ds_read_b128 v[126:129], v73 offset:36896
	ds_read_b128 v[130:133], v73 offset:41472
	ds_read_b128 v[134:137], v73 offset:41504
	ds_read_b128 v[138:141], v70
	ds_read_b128 v[142:145], v70 offset:32
	ds_read_b128 v[170:173], v70 offset:4608
	ds_read_b128 v[174:177], v70 offset:4640
	s_setprio 1
	s_waitcnt lgkmcnt(3)
	v_mfma_f32_32x32x16_bf16 v[50:65], v[138:141], v[122:125], v[50:65]
	s_waitcnt lgkmcnt(1)
	v_mfma_f32_32x32x16_bf16 v[2:17], v[170:173], v[130:133], v[2:17]
	v_mfma_f32_32x32x16_bf16 v[18:33], v[138:141], v[130:133], v[18:33]
	v_mfma_f32_32x32x16_bf16 v[34:49], v[170:173], v[122:125], v[34:49]
	s_setprio 0
	ds_read_b128 v[122:125], v73 offset:36928
	ds_read_b128 v[130:133], v73 offset:41536
	ds_read_b128 v[138:141], v70 offset:64
	ds_read_b128 v[170:173], v70 offset:4672
	s_setprio 1
	v_mfma_f32_32x32x16_bf16 v[50:65], v[142:145], v[126:129], v[50:65]
	s_waitcnt lgkmcnt(4)
	v_mfma_f32_32x32x16_bf16 v[2:17], v[174:177], v[134:137], v[2:17]
	v_mfma_f32_32x32x16_bf16 v[18:33], v[142:145], v[134:137], v[18:33]
	v_mfma_f32_32x32x16_bf16 v[34:49], v[174:177], v[126:129], v[34:49]
	s_setprio 0
	ds_read_b128 v[126:129], v73 offset:36960
	ds_read_b128 v[134:137], v73 offset:41568
	ds_read_b128 v[142:145], v70 offset:96
	ds_read_b128 v[174:177], v70 offset:4704
	s_setprio 1
	s_waitcnt lgkmcnt(5)
	v_mfma_f32_32x32x16_bf16 v[50:65], v[138:141], v[122:125], v[50:65]
	s_waitcnt lgkmcnt(4)
	v_mfma_f32_32x32x16_bf16 v[2:17], v[170:173], v[130:133], v[2:17]
	v_mfma_f32_32x32x16_bf16 v[18:33], v[138:141], v[130:133], v[18:33]
	v_mfma_f32_32x32x16_bf16 v[34:49], v[170:173], v[122:125], v[34:49]
	s_setprio 0
	s_setprio 1
	s_waitcnt lgkmcnt(1)
	v_mfma_f32_32x32x16_bf16 v[50:65], v[142:145], v[126:129], v[50:65]
	s_waitcnt lgkmcnt(0)
	v_mfma_f32_32x32x16_bf16 v[2:17], v[174:177], v[134:137], v[2:17]
	v_mfma_f32_32x32x16_bf16 v[18:33], v[142:145], v[134:137], v[18:33]
	v_mfma_f32_32x32x16_bf16 v[34:49], v[174:177], v[126:129], v[34:49]
	s_setprio 0
	s_barrier
	global_load_dwordx4 v[122:125], v[78:79], off offset:1536
	global_load_dwordx4 v[126:129], v[80:81], off offset:1536
	global_load_dwordx4 v[130:133], v[74:75], off offset:1536
	global_load_dwordx4 v[134:137], v[76:77], off offset:1536
	global_load_dwordx4 v[138:141], v[82:83], off offset:1536
	global_load_dwordx4 v[142:145], v[84:85], off offset:1536
	s_waitcnt vmcnt(15)
	ds_write_b128 v72, v[154:157]
	ds_write_b128 v72, v[146:149] offset:9216
	ds_write_b128 v72, v[150:153] offset:18432
	s_waitcnt vmcnt(13)
	ds_write_b128 v72, v[162:165] offset:27648
	ds_write_b128 v72, v[158:161] offset:36864
	s_waitcnt vmcnt(12)
	ds_write_b128 v72, v[166:169] offset:46080
	ds_read_b128 v[146:149], v66 offset:36864
	ds_read_b128 v[150:153], v66 offset:36896
	ds_read_b128 v[154:157], v66 offset:41472
	ds_read_b128 v[158:161], v66 offset:41504
	ds_read_b128 v[162:165], v71
	ds_read_b128 v[166:169], v71 offset:32
	ds_read_b128 v[170:173], v71 offset:4608
	ds_read_b128 v[174:177], v71 offset:4640
	s_setprio 1
	s_waitcnt lgkmcnt(3)
	v_mfma_f32_32x32x16_bf16 v[50:65], v[162:165], v[146:149], v[50:65]
	s_waitcnt lgkmcnt(1)
	v_mfma_f32_32x32x16_bf16 v[2:17], v[170:173], v[154:157], v[2:17]
	v_mfma_f32_32x32x16_bf16 v[18:33], v[162:165], v[154:157], v[18:33]
	v_mfma_f32_32x32x16_bf16 v[34:49], v[170:173], v[146:149], v[34:49]
	s_setprio 0
	ds_read_b128 v[146:149], v66 offset:36928
	ds_read_b128 v[154:157], v66 offset:41536
	ds_read_b128 v[162:165], v71 offset:64
	ds_read_b128 v[170:173], v71 offset:4672
	s_setprio 1
	v_mfma_f32_32x32x16_bf16 v[50:65], v[166:169], v[150:153], v[50:65]
	s_waitcnt lgkmcnt(4)
	v_mfma_f32_32x32x16_bf16 v[2:17], v[174:177], v[158:161], v[2:17]
	v_mfma_f32_32x32x16_bf16 v[18:33], v[166:169], v[158:161], v[18:33]
	v_mfma_f32_32x32x16_bf16 v[34:49], v[174:177], v[150:153], v[34:49]
	s_setprio 0
	ds_read_b128 v[150:153], v66 offset:36960
	ds_read_b128 v[158:161], v66 offset:41568
	ds_read_b128 v[166:169], v71 offset:96
	ds_read_b128 v[174:177], v71 offset:4704
	s_setprio 1
	s_waitcnt lgkmcnt(5)
	v_mfma_f32_32x32x16_bf16 v[50:65], v[162:165], v[146:149], v[50:65]
	s_waitcnt lgkmcnt(4)
	v_mfma_f32_32x32x16_bf16 v[2:17], v[170:173], v[154:157], v[2:17]
	v_mfma_f32_32x32x16_bf16 v[18:33], v[162:165], v[154:157], v[18:33]
	v_mfma_f32_32x32x16_bf16 v[34:49], v[170:173], v[146:149], v[34:49]
	s_setprio 0
	s_setprio 1
	s_waitcnt lgkmcnt(1)
	v_mfma_f32_32x32x16_bf16 v[50:65], v[166:169], v[150:153], v[50:65]
	s_waitcnt lgkmcnt(0)
	v_mfma_f32_32x32x16_bf16 v[2:17], v[174:177], v[158:161], v[2:17]
	v_mfma_f32_32x32x16_bf16 v[18:33], v[166:169], v[158:161], v[18:33]
	v_mfma_f32_32x32x16_bf16 v[34:49], v[174:177], v[150:153], v[34:49]
	s_setprio 0
	s_barrier
	global_load_dwordx4 v[146:149], v[78:79], off offset:1664
	global_load_dwordx4 v[150:153], v[80:81], off offset:1664
	global_load_dwordx4 v[154:157], v[74:75], off offset:1664
	global_load_dwordx4 v[158:161], v[76:77], off offset:1664
	global_load_dwordx4 v[162:165], v[82:83], off offset:1664
	global_load_dwordx4 v[166:169], v[84:85], off offset:1664
	s_waitcnt vmcnt(15)
	ds_write_b128 v97, v[106:109]
	ds_write_b128 v97, v[98:101] offset:9216
	ds_write_b128 v97, v[102:105] offset:18432
	s_waitcnt vmcnt(13)
	ds_write_b128 v97, v[114:117] offset:27648
	ds_write_b128 v97, v[110:113] offset:36864
	s_waitcnt vmcnt(12)
	ds_write_b128 v97, v[118:121] offset:46080
	ds_read_b128 v[98:101], v73 offset:36864
	ds_read_b128 v[102:105], v73 offset:36896
	ds_read_b128 v[106:109], v73 offset:41472
	ds_read_b128 v[110:113], v73 offset:41504
	ds_read_b128 v[114:117], v70
	ds_read_b128 v[118:121], v70 offset:32
	ds_read_b128 v[170:173], v70 offset:4608
	ds_read_b128 v[174:177], v70 offset:4640
	s_setprio 1
	s_waitcnt lgkmcnt(3)
	v_mfma_f32_32x32x16_bf16 v[50:65], v[114:117], v[98:101], v[50:65]
	s_waitcnt lgkmcnt(1)
	v_mfma_f32_32x32x16_bf16 v[2:17], v[170:173], v[106:109], v[2:17]
	v_mfma_f32_32x32x16_bf16 v[18:33], v[114:117], v[106:109], v[18:33]
	v_mfma_f32_32x32x16_bf16 v[34:49], v[170:173], v[98:101], v[34:49]
	s_setprio 0
	ds_read_b128 v[98:101], v73 offset:36928
	ds_read_b128 v[106:109], v73 offset:41536
	ds_read_b128 v[114:117], v70 offset:64
	ds_read_b128 v[170:173], v70 offset:4672
	s_setprio 1
	v_mfma_f32_32x32x16_bf16 v[50:65], v[118:121], v[102:105], v[50:65]
	s_waitcnt lgkmcnt(4)
	v_mfma_f32_32x32x16_bf16 v[2:17], v[174:177], v[110:113], v[2:17]
	v_mfma_f32_32x32x16_bf16 v[18:33], v[118:121], v[110:113], v[18:33]
	v_mfma_f32_32x32x16_bf16 v[34:49], v[174:177], v[102:105], v[34:49]
	s_setprio 0
	ds_read_b128 v[102:105], v73 offset:36960
	ds_read_b128 v[110:113], v73 offset:41568
	ds_read_b128 v[118:121], v70 offset:96
	ds_read_b128 v[174:177], v70 offset:4704
	s_setprio 1
	s_waitcnt lgkmcnt(5)
	v_mfma_f32_32x32x16_bf16 v[50:65], v[114:117], v[98:101], v[50:65]
	s_waitcnt lgkmcnt(4)
	v_mfma_f32_32x32x16_bf16 v[2:17], v[170:173], v[106:109], v[2:17]
	v_mfma_f32_32x32x16_bf16 v[18:33], v[114:117], v[106:109], v[18:33]
	v_mfma_f32_32x32x16_bf16 v[34:49], v[170:173], v[98:101], v[34:49]
	s_setprio 0
	s_setprio 1
	s_waitcnt lgkmcnt(1)
	v_mfma_f32_32x32x16_bf16 v[50:65], v[118:121], v[102:105], v[50:65]
	s_waitcnt lgkmcnt(0)
	v_mfma_f32_32x32x16_bf16 v[2:17], v[174:177], v[110:113], v[2:17]
	v_mfma_f32_32x32x16_bf16 v[18:33], v[118:121], v[110:113], v[18:33]
	v_mfma_f32_32x32x16_bf16 v[34:49], v[174:177], v[102:105], v[34:49]
	s_setprio 0
	s_barrier
	global_load_dwordx4 v[98:101], v[78:79], off offset:1792
	global_load_dwordx4 v[102:105], v[80:81], off offset:1792
	global_load_dwordx4 v[106:109], v[74:75], off offset:1792
	global_load_dwordx4 v[110:113], v[76:77], off offset:1792
	global_load_dwordx4 v[114:117], v[82:83], off offset:1792
	global_load_dwordx4 v[118:121], v[84:85], off offset:1792
	s_waitcnt vmcnt(15)
	ds_write_b128 v72, v[130:133]
	ds_write_b128 v72, v[122:125] offset:9216
	ds_write_b128 v72, v[126:129] offset:18432
	s_waitcnt vmcnt(13)
	ds_write_b128 v72, v[138:141] offset:27648
	ds_write_b128 v72, v[134:137] offset:36864
	s_waitcnt vmcnt(12)
	ds_write_b128 v72, v[142:145] offset:46080
	ds_read_b128 v[122:125], v66 offset:36864
	ds_read_b128 v[126:129], v66 offset:36896
	ds_read_b128 v[130:133], v66 offset:41472
	ds_read_b128 v[134:137], v66 offset:41504
	ds_read_b128 v[138:141], v71
	ds_read_b128 v[142:145], v71 offset:32
	ds_read_b128 v[170:173], v71 offset:4608
	ds_read_b128 v[174:177], v71 offset:4640
	s_setprio 1
	s_waitcnt lgkmcnt(3)
	v_mfma_f32_32x32x16_bf16 v[50:65], v[138:141], v[122:125], v[50:65]
	s_waitcnt lgkmcnt(1)
	v_mfma_f32_32x32x16_bf16 v[2:17], v[170:173], v[130:133], v[2:17]
	v_mfma_f32_32x32x16_bf16 v[18:33], v[138:141], v[130:133], v[18:33]
	v_mfma_f32_32x32x16_bf16 v[34:49], v[170:173], v[122:125], v[34:49]
	s_setprio 0
	ds_read_b128 v[122:125], v66 offset:36928
	ds_read_b128 v[130:133], v66 offset:41536
	ds_read_b128 v[138:141], v71 offset:64
	ds_read_b128 v[170:173], v71 offset:4672
	s_setprio 1
	v_mfma_f32_32x32x16_bf16 v[50:65], v[142:145], v[126:129], v[50:65]
	s_waitcnt lgkmcnt(4)
	v_mfma_f32_32x32x16_bf16 v[2:17], v[174:177], v[134:137], v[2:17]
	v_mfma_f32_32x32x16_bf16 v[18:33], v[142:145], v[134:137], v[18:33]
	v_mfma_f32_32x32x16_bf16 v[34:49], v[174:177], v[126:129], v[34:49]
	s_setprio 0
	ds_read_b128 v[126:129], v66 offset:36960
	ds_read_b128 v[134:137], v66 offset:41568
	ds_read_b128 v[142:145], v71 offset:96
	ds_read_b128 v[174:177], v71 offset:4704
	s_setprio 1
	s_waitcnt lgkmcnt(5)
	v_mfma_f32_32x32x16_bf16 v[50:65], v[138:141], v[122:125], v[50:65]
	s_waitcnt lgkmcnt(4)
	v_mfma_f32_32x32x16_bf16 v[2:17], v[170:173], v[130:133], v[2:17]
	v_mfma_f32_32x32x16_bf16 v[18:33], v[138:141], v[130:133], v[18:33]
	v_mfma_f32_32x32x16_bf16 v[34:49], v[170:173], v[122:125], v[34:49]
	s_setprio 0
	s_setprio 1
	s_waitcnt lgkmcnt(1)
	v_mfma_f32_32x32x16_bf16 v[50:65], v[142:145], v[126:129], v[50:65]
	s_waitcnt lgkmcnt(0)
	v_mfma_f32_32x32x16_bf16 v[2:17], v[174:177], v[134:137], v[2:17]
	v_mfma_f32_32x32x16_bf16 v[18:33], v[142:145], v[134:137], v[18:33]
	v_mfma_f32_32x32x16_bf16 v[34:49], v[174:177], v[126:129], v[34:49]
	s_setprio 0
	s_barrier
	global_load_dwordx4 v[122:125], v[78:79], off offset:1920
	s_nop 0
	global_load_dwordx4 v[78:81], v[80:81], off offset:1920
	s_nop 0
	global_load_dwordx4 v[126:129], v[74:75], off offset:1920
	s_nop 0
	global_load_dwordx4 v[74:77], v[76:77], off offset:1920
	s_nop 0
	global_load_dwordx4 v[130:133], v[82:83], off offset:1920
	s_nop 0
	global_load_dwordx4 v[82:85], v[84:85], off offset:1920
	s_waitcnt vmcnt(15)
	ds_write_b128 v97, v[154:157]
	ds_write_b128 v97, v[146:149] offset:9216
	ds_write_b128 v97, v[150:153] offset:18432
	s_waitcnt vmcnt(13)
	ds_write_b128 v97, v[162:165] offset:27648
	ds_write_b128 v97, v[158:161] offset:36864
	s_waitcnt vmcnt(12)
	ds_write_b128 v97, v[166:169] offset:46080
	ds_read_b128 v[134:137], v73 offset:36864
	ds_read_b128 v[138:141], v73 offset:36896
	ds_read_b128 v[142:145], v73 offset:41472
	ds_read_b128 v[146:149], v73 offset:41504
	ds_read_b128 v[150:153], v70
	ds_read_b128 v[154:157], v70 offset:32
	ds_read_b128 v[158:161], v70 offset:4608
	ds_read_b128 v[162:165], v70 offset:4640
	s_setprio 1
	s_waitcnt lgkmcnt(3)
	v_mfma_f32_32x32x16_bf16 v[50:65], v[150:153], v[134:137], v[50:65]
	s_waitcnt lgkmcnt(1)
	v_mfma_f32_32x32x16_bf16 v[2:17], v[158:161], v[142:145], v[2:17]
	v_mfma_f32_32x32x16_bf16 v[18:33], v[150:153], v[142:145], v[18:33]
	v_mfma_f32_32x32x16_bf16 v[34:49], v[158:161], v[134:137], v[34:49]
	s_setprio 0
	ds_read_b128 v[134:137], v73 offset:36928
	ds_read_b128 v[142:145], v73 offset:41536
	ds_read_b128 v[150:153], v70 offset:64
	ds_read_b128 v[158:161], v70 offset:4672
	s_setprio 1
	v_mfma_f32_32x32x16_bf16 v[50:65], v[154:157], v[138:141], v[50:65]
	s_waitcnt lgkmcnt(4)
	v_mfma_f32_32x32x16_bf16 v[2:17], v[162:165], v[146:149], v[2:17]
	v_mfma_f32_32x32x16_bf16 v[18:33], v[154:157], v[146:149], v[18:33]
	v_mfma_f32_32x32x16_bf16 v[34:49], v[162:165], v[138:141], v[34:49]
	s_setprio 0
	ds_read_b128 v[138:141], v73 offset:36960
	ds_read_b128 v[146:149], v73 offset:41568
	ds_read_b128 v[154:157], v70 offset:96
	ds_read_b128 v[162:165], v70 offset:4704
	s_setprio 1
	s_waitcnt lgkmcnt(5)
	v_mfma_f32_32x32x16_bf16 v[50:65], v[150:153], v[134:137], v[50:65]
	s_waitcnt lgkmcnt(4)
	v_mfma_f32_32x32x16_bf16 v[2:17], v[158:161], v[142:145], v[2:17]
	v_mfma_f32_32x32x16_bf16 v[18:33], v[150:153], v[142:145], v[18:33]
	v_mfma_f32_32x32x16_bf16 v[34:49], v[158:161], v[134:137], v[34:49]
	s_setprio 0
	s_setprio 1
	s_waitcnt lgkmcnt(1)
	v_mfma_f32_32x32x16_bf16 v[50:65], v[154:157], v[138:141], v[50:65]
	s_waitcnt lgkmcnt(0)
	v_mfma_f32_32x32x16_bf16 v[2:17], v[162:165], v[146:149], v[2:17]
	v_mfma_f32_32x32x16_bf16 v[18:33], v[154:157], v[146:149], v[18:33]
	v_mfma_f32_32x32x16_bf16 v[34:49], v[162:165], v[138:141], v[34:49]
	s_setprio 0
	s_barrier
	s_waitcnt vmcnt(9)
	ds_write_b128 v72, v[106:109]
	ds_write_b128 v72, v[98:101] offset:9216
	ds_write_b128 v72, v[102:105] offset:18432
	s_waitcnt vmcnt(7)
	ds_write_b128 v72, v[114:117] offset:27648
	ds_write_b128 v72, v[110:113] offset:36864
	s_waitcnt vmcnt(6)
	ds_write_b128 v72, v[118:121] offset:46080
	ds_read_b128 v[98:101], v66 offset:36864
	ds_read_b128 v[102:105], v66 offset:36896
	ds_read_b128 v[106:109], v66 offset:41472
	ds_read_b128 v[110:113], v66 offset:41504
	ds_read_b128 v[114:117], v71
	ds_read_b128 v[118:121], v71 offset:32
	ds_read_b128 v[134:137], v71 offset:4608
	ds_read_b128 v[138:141], v71 offset:4640
	s_setprio 1
	s_waitcnt lgkmcnt(3)
	v_mfma_f32_32x32x16_bf16 v[50:65], v[114:117], v[98:101], v[50:65]
	s_waitcnt lgkmcnt(1)
	v_mfma_f32_32x32x16_bf16 v[2:17], v[134:137], v[106:109], v[2:17]
	v_mfma_f32_32x32x16_bf16 v[18:33], v[114:117], v[106:109], v[18:33]
	v_mfma_f32_32x32x16_bf16 v[34:49], v[134:137], v[98:101], v[34:49]
	s_setprio 0
	ds_read_b128 v[98:101], v66 offset:36928
	ds_read_b128 v[106:109], v66 offset:41536
	ds_read_b128 v[114:117], v71 offset:64
	ds_read_b128 v[134:137], v71 offset:4672
	s_setprio 1
	v_mfma_f32_32x32x16_bf16 v[50:65], v[118:121], v[102:105], v[50:65]
	s_waitcnt lgkmcnt(4)
	v_mfma_f32_32x32x16_bf16 v[2:17], v[138:141], v[110:113], v[2:17]
	v_mfma_f32_32x32x16_bf16 v[18:33], v[118:121], v[110:113], v[18:33]
	v_mfma_f32_32x32x16_bf16 v[34:49], v[138:141], v[102:105], v[34:49]
	s_setprio 0
	ds_read_b128 v[102:105], v66 offset:36960
	ds_read_b128 v[110:113], v66 offset:41568
	ds_read_b128 v[118:121], v71 offset:96
	ds_read_b128 v[138:141], v71 offset:4704
	s_setprio 1
	s_waitcnt lgkmcnt(5)
	v_mfma_f32_32x32x16_bf16 v[50:65], v[114:117], v[98:101], v[50:65]
	s_waitcnt lgkmcnt(4)
	v_mfma_f32_32x32x16_bf16 v[2:17], v[134:137], v[106:109], v[2:17]
	v_mfma_f32_32x32x16_bf16 v[18:33], v[114:117], v[106:109], v[18:33]
	v_mfma_f32_32x32x16_bf16 v[34:49], v[134:137], v[98:101], v[34:49]
	s_setprio 0
	s_setprio 1
	s_waitcnt lgkmcnt(1)
	v_mfma_f32_32x32x16_bf16 v[50:65], v[118:121], v[102:105], v[50:65]
	s_waitcnt lgkmcnt(0)
	v_mfma_f32_32x32x16_bf16 v[2:17], v[138:141], v[110:113], v[2:17]
	v_mfma_f32_32x32x16_bf16 v[18:33], v[118:121], v[110:113], v[18:33]
	v_mfma_f32_32x32x16_bf16 v[34:49], v[138:141], v[102:105], v[34:49]
	s_setprio 0
	s_barrier
	s_waitcnt vmcnt(3)
	ds_write_b128 v97, v[126:129]
	ds_write_b128 v97, v[122:125] offset:9216
	ds_write_b128 v97, v[78:81] offset:18432
	s_waitcnt vmcnt(1)
	ds_write_b128 v97, v[130:133] offset:27648
	ds_write_b128 v97, v[74:77] offset:36864
	s_waitcnt vmcnt(0)
	ds_write_b128 v97, v[82:85] offset:46080
	ds_read_b128 v[74:77], v73 offset:36864
	ds_read_b128 v[78:81], v73 offset:36896
	ds_read_b128 v[82:85], v73 offset:41472
	ds_read_b128 v[98:101], v73 offset:41504
	ds_read_b128 v[102:105], v70
	ds_read_b128 v[106:109], v70 offset:32
	ds_read_b128 v[110:113], v70 offset:4608
	ds_read_b128 v[114:117], v70 offset:4640
	s_setprio 1
	s_waitcnt lgkmcnt(3)
	v_mfma_f32_32x32x16_bf16 v[50:65], v[102:105], v[74:77], v[50:65]
	s_waitcnt lgkmcnt(1)
	v_mfma_f32_32x32x16_bf16 v[2:17], v[110:113], v[82:85], v[2:17]
	v_mfma_f32_32x32x16_bf16 v[18:33], v[102:105], v[82:85], v[18:33]
	v_mfma_f32_32x32x16_bf16 v[34:49], v[110:113], v[74:77], v[34:49]
	s_setprio 0
	ds_read_b128 v[74:77], v73 offset:36928
	ds_read_b128 v[82:85], v73 offset:41536
	ds_read_b128 v[102:105], v70 offset:64
	ds_read_b128 v[110:113], v70 offset:4672
	s_setprio 1
	v_mfma_f32_32x32x16_bf16 v[50:65], v[106:109], v[78:81], v[50:65]
	s_waitcnt lgkmcnt(4)
	v_mfma_f32_32x32x16_bf16 v[2:17], v[114:117], v[98:101], v[2:17]
	v_mfma_f32_32x32x16_bf16 v[18:33], v[106:109], v[98:101], v[18:33]
	v_mfma_f32_32x32x16_bf16 v[34:49], v[114:117], v[78:81], v[34:49]
	s_setprio 0
	ds_read_b128 v[78:81], v73 offset:36960
	ds_read_b128 v[98:101], v73 offset:41568
	ds_read_b128 v[106:109], v70 offset:96
	ds_read_b128 v[114:117], v70 offset:4704
	s_setprio 1
	s_waitcnt lgkmcnt(5)
	v_mfma_f32_32x32x16_bf16 v[50:65], v[102:105], v[74:77], v[50:65]
	s_waitcnt lgkmcnt(4)
	v_mfma_f32_32x32x16_bf16 v[2:17], v[110:113], v[82:85], v[2:17]
	v_mfma_f32_32x32x16_bf16 v[18:33], v[102:105], v[82:85], v[18:33]
	v_mfma_f32_32x32x16_bf16 v[34:49], v[110:113], v[74:77], v[34:49]
	s_setprio 0
	s_setprio 1
	s_waitcnt lgkmcnt(1)
	v_mfma_f32_32x32x16_bf16 v[50:65], v[106:109], v[78:81], v[50:65]
	s_waitcnt lgkmcnt(0)
	v_mfma_f32_32x32x16_bf16 v[2:17], v[114:117], v[98:101], v[2:17]
	v_mfma_f32_32x32x16_bf16 v[18:33], v[106:109], v[98:101], v[18:33]
	v_mfma_f32_32x32x16_bf16 v[34:49], v[114:117], v[78:81], v[34:49]
	s_setprio 0
	s_barrier
	ds_read_b128 v[72:75], v66 offset:36864
	ds_read_b128 v[76:79], v66 offset:36896
	ds_read_b128 v[80:83], v66 offset:41472
	ds_read_b128 v[98:101], v66 offset:41504
	ds_read_b128 v[102:105], v71
	ds_read_b128 v[106:109], v71 offset:32
	ds_read_b128 v[110:113], v71 offset:4608
	ds_read_b128 v[114:117], v71 offset:4640
	s_setprio 1
	s_waitcnt lgkmcnt(3)
	v_mfma_f32_32x32x16_bf16 v[50:65], v[102:105], v[72:75], v[50:65]
	s_waitcnt lgkmcnt(1)
	v_mfma_f32_32x32x16_bf16 v[2:17], v[110:113], v[80:83], v[2:17]
	v_mfma_f32_32x32x16_bf16 v[18:33], v[102:105], v[80:83], v[18:33]
	v_mfma_f32_32x32x16_bf16 v[34:49], v[110:113], v[72:75], v[34:49]
	s_setprio 0
	ds_read_b128 v[72:75], v66 offset:36928
	ds_read_b128 v[80:83], v66 offset:41536
	ds_read_b128 v[102:105], v71 offset:64
	ds_read_b128 v[110:113], v71 offset:4672
	s_setprio 1
	v_mfma_f32_32x32x16_bf16 v[50:65], v[106:109], v[76:79], v[50:65]
	s_waitcnt lgkmcnt(4)
	v_mfma_f32_32x32x16_bf16 v[2:17], v[114:117], v[98:101], v[2:17]
	v_mfma_f32_32x32x16_bf16 v[18:33], v[106:109], v[98:101], v[18:33]
	v_mfma_f32_32x32x16_bf16 v[34:49], v[114:117], v[76:79], v[34:49]
	s_setprio 0
	ds_read_b128 v[76:79], v66 offset:36960
	ds_read_b128 v[98:101], v66 offset:41568
	ds_read_b128 v[106:109], v71 offset:96
	ds_read_b128 v[114:117], v71 offset:4704
	s_setprio 1
	s_waitcnt lgkmcnt(5)
	v_mfma_f32_32x32x16_bf16 v[50:65], v[102:105], v[72:75], v[50:65]
	s_waitcnt lgkmcnt(4)
	v_mfma_f32_32x32x16_bf16 v[2:17], v[110:113], v[80:83], v[2:17]
	v_mfma_f32_32x32x16_bf16 v[18:33], v[102:105], v[80:83], v[18:33]
	v_mfma_f32_32x32x16_bf16 v[34:49], v[110:113], v[72:75], v[34:49]
	s_setprio 0
	s_setprio 1
	s_waitcnt lgkmcnt(1)
	v_mfma_f32_32x32x16_bf16 v[50:65], v[106:109], v[76:79], v[50:65]
	s_waitcnt lgkmcnt(0)
	v_mfma_f32_32x32x16_bf16 v[2:17], v[114:117], v[98:101], v[2:17]
	v_mfma_f32_32x32x16_bf16 v[18:33], v[106:109], v[98:101], v[18:33]
	v_mfma_f32_32x32x16_bf16 v[34:49], v[114:117], v[76:79], v[34:49]
	s_setprio 0
	s_add_i32 s3, s12, 0xffffe000
	s_lshr_b32 s3, s3, 12
	s_add_i32 s3, s3, 1
	s_cmp_gt_i32 s14, 63
	s_cselect_b32 s3, s3, 0
	v_lshrrev_b32_e32 v70, 1, v69
	s_mul_i32 s33, s3, 0x3000
	v_lshlrev_b32_e32 v71, 1, v69
	v_and_b32_e32 v70, 16, v70
	s_mul_hi_u32 s14, s3, 0x3000
	s_add_u32 s16, s96, s33
	v_and_b32_e32 v66, 0x5f, v69
	v_and_or_b32 v70, v71, s39, v70
	s_addc_u32 s17, s97, s14
	s_lshl_b64 s[14:15], s[4:5], 2
	v_readlane_b32 s44, v245, 0
	v_mad_u32_u24 v66, v66, s40, v70
	s_add_u32 s16, s16, s14
	v_readlane_b32 s45, v245, 1
	v_readlane_b32 s48, v245, 4
	v_readlane_b32 s49, v245, 5
	s_barrier
	ds_write_b128 v66, v[50:53]
	ds_write_b128 v66, v[54:57] offset:32
	ds_write_b128 v66, v[58:61] offset:64
	ds_write_b128 v66, v[62:65] offset:96
	ds_write_b128 v66, v[34:37] offset:128
	ds_write_b128 v66, v[38:41] offset:160
	ds_write_b128 v66, v[42:45] offset:192
	ds_write_b128 v66, v[46:49] offset:224
	ds_write_b128 v66, v[18:21] offset:33280
	ds_write_b128 v66, v[22:25] offset:33312
	ds_write_b128 v66, v[26:29] offset:33344
	ds_write_b128 v66, v[30:33] offset:33376
	ds_write_b128 v66, v[2:5] offset:33408
	ds_write_b128 v66, v[6:9] offset:33440
	ds_write_b128 v66, v[10:13] offset:33472
	ds_write_b128 v66, v[14:17] offset:33504
	s_addc_u32 s17, s17, s15
	v_lshlrev_b32_e32 v66, 4, v68
	s_mov_b64 s[44:45], s[48:49]
	v_lshl_add_u64 v[2:3], s[16:17], 0, v[66:67]
	s_add_u32 s16, s44, s14
	v_ashrrev_i32_e32 v59, 2, v69
	s_addc_u32 s17, s45, s15
	s_add_i32 s3, s3, 5
	s_add_i32 s33, s33, 0xf000
	v_and_b32_e32 v58, -16, v59
	s_mul_hi_u32 s3, s3, 0x3000
	s_add_u32 s33, s96, s33
	v_add_u32_e32 v60, s12, v58
	s_addc_u32 s3, s97, s3
	v_add_u32_e32 v6, 0xffffe000, v60
	v_ashrrev_i32_e32 v61, 31, v60
	v_cmp_gt_i32_e32 vcc, s41, v60
	s_add_u32 s44, s33, s14
	s_addc_u32 s45, s3, s15
	v_cndmask_b32_e32 v7, 0, v61, vcc
	v_cndmask_b32_e32 v6, v6, v60, vcc
	v_cndmask_b32_e32 v9, v1, v86, vcc
	v_cndmask_b32_e32 v8, v87, v88, vcc
	v_lshlrev_b64 v[6:7], 12, v[6:7]
	v_add_co_u32_e32 v2, vcc, s41, v2
	v_lshl_add_u64 v[4:5], s[44:45], 0, v[66:67]
	v_lshl_add_u64 v[6:7], v[8:9], 0, v[6:7]
	v_addc_co_u32_e32 v3, vcc, 0, v3, vcc
	v_lshl_add_u64 v[6:7], v[6:7], 0, s[14:15]
	v_add_co_u32_e32 v10, vcc, s42, v4
	v_lshl_add_u64 v[6:7], v[6:7], 0, v[66:67]
	s_nop 0
	v_addc_co_u32_e32 v11, vcc, 0, v5, vcc
	s_waitcnt lgkmcnt(0)
	s_barrier
	s_mov_b64 s[98:99], 0x2000
	v_lshl_add_u64 v[246:247], v[6:7], 0, s[98:99]
	global_load_dwordx4 v[6:9], v[6:7], off
	s_nop 0
	global_load_dwordx4 v[2:5], v[2:3], off
	s_nop 0
	global_load_dwordx4 v[10:13], v[10:11], off
	s_nop 0
	global_load_dwordx4 v[14:17], v66, s[16:17]
	global_load_dwordx4 v[120:123], v[246:247], off offset:-4096
	global_load_dwordx4 v[124:127], v[246:247], off
	v_lshl_add_u64 v[246:247], v[246:247], 0, s[98:99]
	global_load_dwordx4 v[128:131], v[246:247], off offset:-4096
	global_load_dwordx4 v[132:135], v[246:247], off
	v_lshl_add_u64 v[246:247], v[246:247], 0, s[98:99]
	global_load_dwordx4 v[136:139], v[246:247], off offset:-4096
	global_load_dwordx4 v[140:143], v[246:247], off
	v_lshl_add_u64 v[246:247], v[246:247], 0, s[98:99]
	global_load_dwordx4 v[144:147], v[246:247], off offset:-4096
	global_load_dwordx4 v[148:151], v[246:247], off
	v_lshl_add_u64 v[246:247], v[246:247], 0, s[98:99]
	global_load_dwordx4 v[152:155], v[246:247], off offset:-4096
	global_load_dwordx4 v[156:159], v[246:247], off
	v_lshl_add_u64 v[246:247], v[246:247], 0, s[98:99]
	global_load_dwordx4 v[160:163], v[246:247], off offset:-4096
	global_load_dwordx4 v[164:167], v[246:247], off
	v_lshl_add_u64 v[246:247], v[246:247], 0, s[98:99]
	global_load_dwordx4 v[168:171], v[246:247], off offset:-4096
	global_load_dwordx4 v[172:175], v[246:247], off
	v_lshl_add_u64 v[246:247], v[246:247], 0, s[98:99]
	v_lshlrev_b64 v[18:19], 12, v[60:61]
	v_lshl_add_u64 v[18:19], s[74:75], 0, v[18:19]
	v_lshl_add_u64 v[18:19], v[18:19], 0, s[14:15]
	v_mad_u64_u32 v[72:73], s[16:17], v58, s40, v[66:67]
	v_lshl_add_u64 v[26:27], v[18:19], 0, v[66:67]
	v_lshlrev_b64 v[18:19], 11, v[60:61]
	v_lshl_add_u64 v[18:19], s[10:11], 0, v[18:19]
	s_lshl_b64 s[16:17], s[4:5], 1
	v_lshl_add_u64 v[18:19], v[18:19], 0, s[16:17]
	v_lshlrev_b32_e32 v62, 3, v68
	v_mov_b32_e32 v63, v67
	v_or_b32_e32 v30, 1, v60
	v_lshl_add_u64 v[28:29], v[18:19], 0, v[62:63]
	v_add_u32_e32 v18, 0xffffe001, v60
	v_ashrrev_i32_e32 v31, 31, v30
	v_cmp_gt_i32_e32 vcc, s41, v30
	v_or_b32_e32 v36, 5, v60
	v_add_u32_e32 v40, 0xffffe005, v60
	v_cndmask_b32_e32 v19, 0, v31, vcc
	v_cndmask_b32_e32 v18, v18, v30, vcc
	v_lshlrev_b64 v[24:25], 12, v[18:19]
	ds_read_b128 v[18:21], v72
	v_cndmask_b32_e32 v23, v1, v86, vcc
	v_cndmask_b32_e32 v22, v87, v88, vcc
	v_lshl_add_u64 v[22:23], v[22:23], 0, v[24:25]
	v_lshl_add_u64 v[22:23], v[22:23], 0, s[14:15]
	v_lshl_add_u64 v[32:33], v[22:23], 0, v[66:67]
	ds_read_b128 v[22:25], v72 offset:1040
	v_ashrrev_i32_e32 v37, 31, v36
	v_or_b32_e32 v44, 7, v60
	v_add_u32_e32 v48, 0xffffe007, v60
	v_ashrrev_i32_e32 v45, 31, v44
	v_or_b32_e32 v52, 9, v60
	v_add_u32_e32 v56, 0xffffe009, v60
	v_ashrrev_i32_e32 v53, 31, v52
	v_or_b32_e32 v76, 11, v60
	v_add_u32_e32 v61, 0xffffe00b, v60
	v_ashrrev_i32_e32 v77, 31, v76
	v_or_b32_e32 v84, 13, v60
	v_ashrrev_i32_e32 v85, 31, v84
	v_or_b32_e32 v59, 15, v59
	v_and_b32_e32 v97, 32, v69
	v_and_b32_e32 v110, 16, v69
	v_and_b32_e32 v111, 8, v69
	v_and_b32_e32 v112, 4, v69
	v_readlane_b32 s46, v245, 2
	v_readlane_b32 s47, v245, 3
	v_readlane_b32 s50, v245, 6
	v_readlane_b32 s51, v245, 7
	v_readlane_b32 s52, v245, 8
	v_readlane_b32 s53, v245, 9
	v_readlane_b32 s54, v245, 10
	v_readlane_b32 s55, v245, 11
	v_readlane_b32 s56, v245, 12
	v_readlane_b32 s57, v245, 13
	v_readlane_b32 s58, v245, 14
	v_readlane_b32 s59, v245, 15
	s_waitcnt vmcnt(15)
	v_pk_add_f32 v[10:11], v[10:11], 1.0 op_sel_hi:[1,0]
	v_pk_add_f32 v[12:13], v[12:13], 1.0 op_sel_hi:[1,0]
	s_waitcnt lgkmcnt(1)
	v_pk_fma_f32 v[6:7], v[2:3], v[18:19], v[6:7]
	s_waitcnt vmcnt(14)
	v_pk_mul_f32 v[64:65], v[14:15], v[10:11]
	v_pk_fma_f32 v[8:9], v[4:5], v[20:21], v[8:9]
	v_pk_mul_f32 v[70:71], v[16:17], v[12:13]
	v_pk_mul_f32 v[10:11], v[64:65], v[6:7]
	v_pk_mul_f32 v[12:13], v[70:71], v[8:9]
	v_cvt_pk_bf16_f32 v10, v10, v11
	v_cvt_pk_bf16_f32 v11, v12, v13
	global_store_dwordx4 v[26:27], v[6:9], off
	global_store_dwordx2 v[28:29], v[10:11], off
	v_or_b32_e32 v26, 2, v60
	v_lshlrev_b64 v[14:15], 12, v[30:31]
	v_add_u32_e32 v18, 0xffffe002, v60
	v_ashrrev_i32_e32 v27, 31, v26
	v_cmp_gt_i32_e32 vcc, s41, v26
	v_lshl_add_u64 v[14:15], s[74:75], 0, v[14:15]
	v_lshlrev_b64 v[16:17], 11, v[30:31]
	v_cndmask_b32_e32 v19, 0, v27, vcc
	v_cndmask_b32_e32 v18, v18, v26, vcc
	v_lshl_add_u64 v[14:15], v[14:15], 0, s[14:15]
	v_cndmask_b32_e32 v21, v1, v86, vcc
	v_cndmask_b32_e32 v20, v87, v88, vcc
	v_lshl_add_u64 v[16:17], s[10:11], 0, v[16:17]
	v_lshlrev_b64 v[18:19], 12, v[18:19]
	v_lshl_add_u64 v[14:15], v[14:15], 0, v[66:67]
	v_lshl_add_u64 v[18:19], v[20:21], 0, v[18:19]
	v_lshl_add_u64 v[16:17], v[16:17], 0, s[16:17]
	v_lshl_add_u64 v[18:19], v[18:19], 0, s[14:15]
	v_lshl_add_u64 v[16:17], v[16:17], 0, v[62:63]
	v_lshl_add_u64 v[18:19], v[18:19], 0, v[66:67]
	v_or_b32_e32 v28, 3, v60
	v_add_u32_e32 v32, 0xffffe003, v60
	v_ashrrev_i32_e32 v29, 31, v28
	v_cmp_gt_i32_e32 vcc, s41, v28
	v_lshlrev_b64 v[30:31], 12, v[26:27]
	v_lshlrev_b64 v[26:27], 11, v[26:27]
	v_cndmask_b32_e32 v33, 0, v29, vcc
	v_cndmask_b32_e32 v32, v32, v28, vcc
	v_cndmask_b32_e32 v35, v1, v86, vcc
	v_cndmask_b32_e32 v34, v87, v88, vcc
	v_lshl_add_u64 v[30:31], s[74:75], 0, v[30:31]
	v_lshl_add_u64 v[26:27], s[10:11], 0, v[26:27]
	v_lshlrev_b64 v[32:33], 12, v[32:33]
	v_lshl_add_u64 v[32:33], v[34:35], 0, v[32:33]
	v_lshl_add_u64 v[30:31], v[30:31], 0, s[14:15]
	v_lshl_add_u64 v[26:27], v[26:27], 0, s[16:17]
	v_lshl_add_u64 v[32:33], v[32:33], 0, s[14:15]
	v_lshl_add_u64 v[30:31], v[30:31], 0, v[66:67]
	v_lshl_add_u64 v[26:27], v[26:27], 0, v[62:63]
	v_lshl_add_u64 v[32:33], v[32:33], 0, v[66:67]
	v_or_b32_e32 v34, 4, v60
	v_ashrrev_i32_e32 v35, 31, v34
	v_cmp_gt_i32_e32 vcc, s41, v34
	v_lshlrev_b64 v[38:39], 12, v[34:35]
	v_lshl_add_u64 v[38:39], s[74:75], 0, v[38:39]
	v_lshl_add_u64 v[38:39], v[38:39], 0, s[14:15]
	v_lshl_add_u64 v[38:39], v[38:39], 0, v[66:67]
	v_pk_mul_f32 v[6:7], v[6:7], v[6:7]
	v_pk_mul_f32 v[8:9], v[8:9], v[8:9]
	v_add_f32_e32 v6, v6, v7
	v_add_f32_e32 v6, v6, v8
	s_waitcnt vmcnt(15) lgkmcnt(0)
	v_pk_fma_f32 v[10:11], v[2:3], v[22:23], v[120:121]
	v_pk_fma_f32 v[12:13], v[4:5], v[24:25], v[122:123]
	global_store_dwordx4 v[14:15], v[10:13], off
	v_pk_mul_f32 v[14:15], v[64:65], v[10:11]
	v_pk_mul_f32 v[20:21], v[70:71], v[12:13]
	v_cvt_pk_bf16_f32 v14, v14, v15
	v_cvt_pk_bf16_f32 v15, v20, v21
	global_store_dwordx2 v[16:17], v[14:15], off
	global_load_dwordx4 v[120:123], v[246:247], off offset:-4096
	ds_read_b128 v[18:21], v72 offset:2080
	ds_read_b128 v[22:25], v72 offset:3120
	s_waitcnt vmcnt(17) lgkmcnt(1)
	v_pk_fma_f32 v[14:15], v[2:3], v[18:19], v[124:125]
	v_pk_fma_f32 v[16:17], v[4:5], v[20:21], v[126:127]
	v_pk_mul_f32 v[18:19], v[64:65], v[14:15]
	v_pk_mul_f32 v[20:21], v[70:71], v[16:17]
	v_cvt_pk_bf16_f32 v18, v18, v19
	v_cvt_pk_bf16_f32 v19, v20, v21
	global_store_dwordx4 v[30:31], v[14:17], off
	global_store_dwordx2 v[26:27], v[18:19], off
	v_add_u32_e32 v30, 0xffffe004, v60
	v_lshlrev_b64 v[26:27], 12, v[28:29]
	v_lshlrev_b64 v[28:29], 11, v[28:29]
	v_cndmask_b32_e32 v31, 0, v35, vcc
	v_cndmask_b32_e32 v30, v30, v34, vcc
	v_cndmask_b32_e32 v33, v1, v86, vcc
	v_cndmask_b32_e32 v32, v87, v88, vcc
	v_lshl_add_u64 v[26:27], s[74:75], 0, v[26:27]
	v_lshl_add_u64 v[28:29], s[10:11], 0, v[28:29]
	v_lshlrev_b64 v[30:31], 12, v[30:31]
	v_lshl_add_u64 v[30:31], v[32:33], 0, v[30:31]
	v_lshl_add_u64 v[26:27], v[26:27], 0, s[14:15]
	v_lshl_add_u64 v[28:29], v[28:29], 0, s[16:17]
	v_lshl_add_u64 v[30:31], v[30:31], 0, s[14:15]
	v_lshl_add_u64 v[26:27], v[26:27], 0, v[66:67]
	v_lshl_add_u64 v[28:29], v[28:29], 0, v[62:63]
	v_lshl_add_u64 v[30:31], v[30:31], 0, v[66:67]
	v_cmp_gt_i32_e32 vcc, s41, v36
	v_lshlrev_b64 v[34:35], 11, v[34:35]
	v_lshl_add_u64 v[34:35], s[10:11], 0, v[34:35]
	v_cndmask_b32_e32 v41, 0, v37, vcc
	v_cndmask_b32_e32 v40, v40, v36, vcc
	v_cndmask_b32_e32 v43, v1, v86, vcc
	v_cndmask_b32_e32 v42, v87, v88, vcc
	v_lshlrev_b64 v[40:41], 12, v[40:41]
	v_lshl_add_u64 v[40:41], v[42:43], 0, v[40:41]
	v_lshl_add_u64 v[34:35], v[34:35], 0, s[16:17]
	v_lshl_add_u64 v[40:41], v[40:41], 0, s[14:15]
	v_lshl_add_u64 v[34:35], v[34:35], 0, v[62:63]
	v_lshl_add_u64 v[40:41], v[40:41], 0, v[66:67]
	v_or_b32_e32 v42, 6, v60
	v_ashrrev_i32_e32 v43, 31, v42
	v_cmp_gt_i32_e32 vcc, s41, v42
	v_lshlrev_b64 v[46:47], 12, v[42:43]
	v_lshl_add_u64 v[46:47], s[74:75], 0, v[46:47]
	v_lshl_add_u64 v[46:47], v[46:47], 0, s[14:15]
	v_lshl_add_u64 v[46:47], v[46:47], 0, v[66:67]
	s_waitcnt vmcnt(18) lgkmcnt(0)
	v_pk_fma_f32 v[18:19], v[2:3], v[22:23], v[128:129]
	v_pk_fma_f32 v[20:21], v[4:5], v[24:25], v[130:131]
	v_pk_mul_f32 v[22:23], v[64:65], v[18:19]
	v_pk_mul_f32 v[24:25], v[70:71], v[20:21]
	v_cvt_pk_bf16_f32 v22, v22, v23
	v_cvt_pk_bf16_f32 v23, v24, v25
	global_store_dwordx4 v[26:27], v[18:21], off
	global_store_dwordx2 v[28:29], v[22:23], off
	ds_read_b128 v[26:29], v72 offset:4160
	ds_read_b128 v[30:33], v72 offset:5200
	s_waitcnt vmcnt(19) lgkmcnt(1)
	v_pk_fma_f32 v[22:23], v[2:3], v[26:27], v[132:133]
	v_pk_fma_f32 v[24:25], v[4:5], v[28:29], v[134:135]
	v_pk_mul_f32 v[26:27], v[64:65], v[22:23]
	v_pk_mul_f32 v[28:29], v[70:71], v[24:25]
	v_cvt_pk_bf16_f32 v26, v26, v27
	v_cvt_pk_bf16_f32 v27, v28, v29
	global_store_dwordx4 v[38:39], v[22:25], off
	global_store_dwordx2 v[34:35], v[26:27], off
	v_add_u32_e32 v38, 0xffffe006, v60
	v_lshlrev_b64 v[34:35], 12, v[36:37]
	v_lshlrev_b64 v[36:37], 11, v[36:37]
	v_cndmask_b32_e32 v39, 0, v43, vcc
	v_cndmask_b32_e32 v38, v38, v42, vcc
	v_cndmask_b32_e32 v41, v1, v86, vcc
	v_cndmask_b32_e32 v40, v87, v88, vcc
	v_lshl_add_u64 v[34:35], s[74:75], 0, v[34:35]
	v_lshl_add_u64 v[36:37], s[10:11], 0, v[36:37]
	v_lshlrev_b64 v[38:39], 12, v[38:39]
	v_lshl_add_u64 v[38:39], v[40:41], 0, v[38:39]
	v_lshl_add_u64 v[34:35], v[34:35], 0, s[14:15]
	v_lshl_add_u64 v[36:37], v[36:37], 0, s[16:17]
	v_lshl_add_u64 v[38:39], v[38:39], 0, s[14:15]
	v_lshl_add_u64 v[34:35], v[34:35], 0, v[66:67]
	v_lshl_add_u64 v[36:37], v[36:37], 0, v[62:63]
	v_lshl_add_u64 v[38:39], v[38:39], 0, v[66:67]
	v_cmp_gt_i32_e32 vcc, s41, v44
	v_lshlrev_b64 v[42:43], 11, v[42:43]
	v_lshl_add_u64 v[42:43], s[10:11], 0, v[42:43]
	v_cndmask_b32_e32 v49, 0, v45, vcc
	v_cndmask_b32_e32 v48, v48, v44, vcc
	v_cndmask_b32_e32 v51, v1, v86, vcc
	v_cndmask_b32_e32 v50, v87, v88, vcc
	v_lshlrev_b64 v[48:49], 12, v[48:49]
	v_lshl_add_u64 v[48:49], v[50:51], 0, v[48:49]
	v_lshl_add_u64 v[42:43], v[42:43], 0, s[16:17]
	v_lshl_add_u64 v[48:49], v[48:49], 0, s[14:15]
	v_lshl_add_u64 v[42:43], v[42:43], 0, v[62:63]
	v_lshl_add_u64 v[48:49], v[48:49], 0, v[66:67]
	v_or_b32_e32 v50, 8, v60
	v_ashrrev_i32_e32 v51, 31, v50
	v_cmp_gt_i32_e32 vcc, s41, v50
	v_lshlrev_b64 v[54:55], 12, v[50:51]
	v_lshl_add_u64 v[54:55], s[74:75], 0, v[54:55]
	v_lshl_add_u64 v[54:55], v[54:55], 0, s[14:15]
	v_lshl_add_u64 v[54:55], v[54:55], 0, v[66:67]
	s_waitcnt vmcnt(20) lgkmcnt(0)
	v_pk_fma_f32 v[26:27], v[2:3], v[30:31], v[136:137]
	v_pk_fma_f32 v[28:29], v[4:5], v[32:33], v[138:139]
	v_pk_mul_f32 v[30:31], v[64:65], v[26:27]
	v_pk_mul_f32 v[32:33], v[70:71], v[28:29]
	v_cvt_pk_bf16_f32 v30, v30, v31
	v_cvt_pk_bf16_f32 v31, v32, v33
	global_store_dwordx4 v[34:35], v[26:29], off
	global_store_dwordx2 v[36:37], v[30:31], off
	ds_read_b128 v[34:37], v72 offset:6240
	ds_read_b128 v[38:41], v72 offset:7280
	s_waitcnt vmcnt(21) lgkmcnt(1)
	v_pk_fma_f32 v[30:31], v[2:3], v[34:35], v[140:141]
	v_pk_fma_f32 v[32:33], v[4:5], v[36:37], v[142:143]
	v_pk_mul_f32 v[34:35], v[64:65], v[30:31]
	v_pk_mul_f32 v[36:37], v[70:71], v[32:33]
	v_cvt_pk_bf16_f32 v34, v34, v35
	v_cvt_pk_bf16_f32 v35, v36, v37
	global_store_dwordx4 v[46:47], v[30:33], off
	global_store_dwordx2 v[42:43], v[34:35], off
	v_add_u32_e32 v46, 0xffffe008, v60
	v_lshlrev_b64 v[42:43], 12, v[44:45]
	v_lshlrev_b64 v[44:45], 11, v[44:45]
	v_cndmask_b32_e32 v47, 0, v51, vcc
	v_cndmask_b32_e32 v46, v46, v50, vcc
	v_cndmask_b32_e32 v49, v1, v86, vcc
	v_cndmask_b32_e32 v48, v87, v88, vcc
	v_lshl_add_u64 v[42:43], s[74:75], 0, v[42:43]
	v_lshl_add_u64 v[44:45], s[10:11], 0, v[44:45]
	v_lshlrev_b64 v[46:47], 12, v[46:47]
	v_lshl_add_u64 v[46:47], v[48:49], 0, v[46:47]
	v_lshl_add_u64 v[42:43], v[42:43], 0, s[14:15]
	v_lshl_add_u64 v[44:45], v[44:45], 0, s[16:17]
	v_lshl_add_u64 v[46:47], v[46:47], 0, s[14:15]
	v_lshl_add_u64 v[42:43], v[42:43], 0, v[66:67]
	v_lshl_add_u64 v[44:45], v[44:45], 0, v[62:63]
	v_lshl_add_u64 v[46:47], v[46:47], 0, v[66:67]
	v_cmp_gt_i32_e32 vcc, s41, v52
	v_lshlrev_b64 v[50:51], 11, v[50:51]
	v_lshl_add_u64 v[50:51], s[10:11], 0, v[50:51]
	v_cndmask_b32_e32 v57, 0, v53, vcc
	v_cndmask_b32_e32 v56, v56, v52, vcc
	v_cndmask_b32_e32 v75, v1, v86, vcc
	v_cndmask_b32_e32 v74, v87, v88, vcc
	v_lshlrev_b64 v[56:57], 12, v[56:57]
	v_lshl_add_u64 v[56:57], v[74:75], 0, v[56:57]
	v_lshl_add_u64 v[50:51], v[50:51], 0, s[16:17]
	v_lshl_add_u64 v[56:57], v[56:57], 0, s[14:15]
	v_lshl_add_u64 v[50:51], v[50:51], 0, v[62:63]
	v_lshl_add_u64 v[56:57], v[56:57], 0, v[66:67]
	v_or_b32_e32 v74, 10, v60
	v_ashrrev_i32_e32 v75, 31, v74
	v_cmp_gt_i32_e32 vcc, s41, v74
	v_lshlrev_b64 v[78:79], 12, v[74:75]
	v_lshl_add_u64 v[78:79], s[74:75], 0, v[78:79]
	v_lshl_add_u64 v[78:79], v[78:79], 0, s[14:15]
	v_lshl_add_u64 v[78:79], v[78:79], 0, v[66:67]
	s_waitcnt vmcnt(22) lgkmcnt(0)
	v_pk_fma_f32 v[34:35], v[2:3], v[38:39], v[144:145]
	v_pk_fma_f32 v[36:37], v[4:5], v[40:41], v[146:147]
	v_pk_mul_f32 v[38:39], v[64:65], v[34:35]
	v_pk_mul_f32 v[40:41], v[70:71], v[36:37]
	v_cvt_pk_bf16_f32 v38, v38, v39
	v_cvt_pk_bf16_f32 v39, v40, v41
	global_store_dwordx4 v[42:43], v[34:37], off
	global_store_dwordx2 v[44:45], v[38:39], off
	ds_read_b128 v[42:45], v72 offset:8320
	ds_read_b128 v[46:49], v72 offset:9360
	s_waitcnt vmcnt(23) lgkmcnt(1)
	v_pk_fma_f32 v[38:39], v[2:3], v[42:43], v[148:149]
	v_pk_fma_f32 v[40:41], v[4:5], v[44:45], v[150:151]
	v_pk_mul_f32 v[42:43], v[64:65], v[38:39]
	v_pk_mul_f32 v[44:45], v[70:71], v[40:41]
	v_cvt_pk_bf16_f32 v42, v42, v43
	v_cvt_pk_bf16_f32 v43, v44, v45
	global_store_dwordx4 v[54:55], v[38:41], off
	global_store_dwordx2 v[50:51], v[42:43], off
	v_add_u32_e32 v54, 0xffffe00a, v60
	v_lshlrev_b64 v[50:51], 12, v[52:53]
	v_lshlrev_b64 v[52:53], 11, v[52:53]
	v_cndmask_b32_e32 v55, 0, v75, vcc
	v_cndmask_b32_e32 v54, v54, v74, vcc
	v_cndmask_b32_e32 v57, v1, v86, vcc
	v_cndmask_b32_e32 v56, v87, v88, vcc
	v_lshl_add_u64 v[50:51], s[74:75], 0, v[50:51]
	v_lshl_add_u64 v[52:53], s[10:11], 0, v[52:53]
	v_lshlrev_b64 v[54:55], 12, v[54:55]
	v_lshl_add_u64 v[54:55], v[56:57], 0, v[54:55]
	v_lshl_add_u64 v[50:51], v[50:51], 0, s[14:15]
	v_lshl_add_u64 v[52:53], v[52:53], 0, s[16:17]
	v_lshl_add_u64 v[54:55], v[54:55], 0, s[14:15]
	v_lshl_add_u64 v[50:51], v[50:51], 0, v[66:67]
	v_lshl_add_u64 v[52:53], v[52:53], 0, v[62:63]
	v_lshl_add_u64 v[54:55], v[54:55], 0, v[66:67]
	v_cmp_gt_i32_e32 vcc, s41, v76
	v_lshlrev_b64 v[74:75], 11, v[74:75]
	v_lshl_add_u64 v[74:75], s[10:11], 0, v[74:75]
	v_cndmask_b32_e32 v81, 0, v77, vcc
	v_cndmask_b32_e32 v80, v61, v76, vcc
	v_cndmask_b32_e32 v83, v1, v86, vcc
	v_cndmask_b32_e32 v82, v87, v88, vcc
	v_lshlrev_b64 v[80:81], 12, v[80:81]
	v_lshl_add_u64 v[80:81], v[82:83], 0, v[80:81]
	v_lshl_add_u64 v[74:75], v[74:75], 0, s[16:17]
	v_lshl_add_u64 v[80:81], v[80:81], 0, s[14:15]
	v_lshl_add_u64 v[74:75], v[74:75], 0, v[62:63]
	v_lshl_add_u64 v[80:81], v[80:81], 0, v[66:67]
	v_or_b32_e32 v82, 12, v60
	v_add_u32_e32 v61, 0xffffe00c, v60
	v_ashrrev_i32_e32 v83, 31, v82
	v_cmp_gt_i32_e32 vcc, s41, v82
	v_lshlrev_b64 v[98:99], 12, v[82:83]
	v_lshl_add_u64 v[98:99], s[74:75], 0, v[98:99]
	v_lshl_add_u64 v[98:99], v[98:99], 0, s[14:15]
	v_lshl_add_u64 v[98:99], v[98:99], 0, v[66:67]
	s_waitcnt vmcnt(24) lgkmcnt(0)
	v_pk_fma_f32 v[42:43], v[2:3], v[46:47], v[152:153]
	v_pk_fma_f32 v[44:45], v[4:5], v[48:49], v[154:155]
	v_pk_mul_f32 v[46:47], v[64:65], v[42:43]
	v_pk_mul_f32 v[48:49], v[70:71], v[44:45]
	v_cvt_pk_bf16_f32 v46, v46, v47
	v_cvt_pk_bf16_f32 v47, v48, v49
	global_store_dwordx4 v[50:51], v[42:45], off
	global_store_dwordx2 v[52:53], v[46:47], off
	ds_read_b128 v[50:53], v72 offset:10400
	ds_read_b128 v[54:57], v72 offset:11440
	s_waitcnt vmcnt(25) lgkmcnt(1)
	v_pk_fma_f32 v[46:47], v[2:3], v[50:51], v[156:157]
	v_pk_fma_f32 v[48:49], v[4:5], v[52:53], v[158:159]
	v_pk_mul_f32 v[50:51], v[64:65], v[46:47]
	v_pk_mul_f32 v[52:53], v[70:71], v[48:49]
	v_cvt_pk_bf16_f32 v50, v50, v51
	v_cvt_pk_bf16_f32 v51, v52, v53
	global_store_dwordx4 v[78:79], v[46:49], off
	global_store_dwordx2 v[74:75], v[50:51], off
	v_lshlrev_b64 v[74:75], 12, v[76:77]
	v_lshlrev_b64 v[76:77], 11, v[76:77]
	v_cndmask_b32_e32 v79, 0, v83, vcc
	v_cndmask_b32_e32 v78, v61, v82, vcc
	v_cndmask_b32_e32 v81, v1, v86, vcc
	v_cndmask_b32_e32 v80, v87, v88, vcc
	v_lshl_add_u64 v[74:75], s[74:75], 0, v[74:75]
	v_lshl_add_u64 v[76:77], s[10:11], 0, v[76:77]
	v_lshlrev_b64 v[78:79], 12, v[78:79]
	v_lshl_add_u64 v[78:79], v[80:81], 0, v[78:79]
	v_lshl_add_u64 v[74:75], v[74:75], 0, s[14:15]
	v_lshl_add_u64 v[76:77], v[76:77], 0, s[16:17]
	v_lshl_add_u64 v[78:79], v[78:79], 0, s[14:15]
	v_lshl_add_u64 v[74:75], v[74:75], 0, v[66:67]
	v_lshl_add_u64 v[76:77], v[76:77], 0, v[62:63]
	v_lshl_add_u64 v[78:79], v[78:79], 0, v[66:67]
	v_add_u32_e32 v61, 0xffffe00d, v60
	v_cmp_gt_i32_e32 vcc, s41, v84
	v_lshlrev_b64 v[82:83], 11, v[82:83]
	v_lshl_add_u64 v[82:83], s[10:11], 0, v[82:83]
	v_cndmask_b32_e32 v101, 0, v85, vcc
	v_cndmask_b32_e32 v100, v61, v84, vcc
	v_cndmask_b32_e32 v103, v1, v86, vcc
	v_cndmask_b32_e32 v102, v87, v88, vcc
	v_lshlrev_b64 v[100:101], 12, v[100:101]
	v_lshl_add_u64 v[100:101], v[102:103], 0, v[100:101]
	v_lshl_add_u64 v[82:83], v[82:83], 0, s[16:17]
	v_lshl_add_u64 v[100:101], v[100:101], 0, s[14:15]
	v_lshl_add_u64 v[82:83], v[82:83], 0, v[62:63]
	v_lshl_add_u64 v[100:101], v[100:101], 0, v[66:67]
	v_cmp_lt_i32_e32 vcc, v91, v90
	v_or_b32_e32 v102, 14, v60
	v_ashrrev_i32_e32 v103, 31, v102
	v_cndmask_b32_e32 v73, v89, v91, vcc
	v_cmp_gt_i32_e32 vcc, s41, v102
	v_lshlrev_b32_e32 v114, 2, v73
	s_waitcnt vmcnt(26) lgkmcnt(0)
	v_pk_fma_f32 v[50:51], v[2:3], v[54:55], v[160:161]
	v_pk_fma_f32 v[52:53], v[4:5], v[56:57], v[162:163]
	v_pk_mul_f32 v[54:55], v[64:65], v[50:51]
	v_pk_mul_f32 v[56:57], v[70:71], v[52:53]
	v_cvt_pk_bf16_f32 v54, v54, v55
	v_cvt_pk_bf16_f32 v55, v56, v57
	global_store_dwordx4 v[74:75], v[50:53], off
	global_store_dwordx2 v[76:77], v[54:55], off
	ds_read_b128 v[74:77], v72 offset:12480
	ds_read_b128 v[78:81], v72 offset:13520
	s_waitcnt vmcnt(27) lgkmcnt(1)
	v_pk_fma_f32 v[54:55], v[2:3], v[74:75], v[164:165]
	v_pk_fma_f32 v[56:57], v[4:5], v[76:77], v[166:167]
	v_pk_mul_f32 v[74:75], v[64:65], v[54:55]
	v_pk_mul_f32 v[76:77], v[70:71], v[56:57]
	v_cvt_pk_bf16_f32 v74, v74, v75
	v_cvt_pk_bf16_f32 v75, v76, v77
	global_store_dwordx4 v[98:99], v[54:57], off
	global_store_dwordx2 v[82:83], v[74:75], off
	v_add_u32_e32 v98, 0xffffe00e, v60
	v_lshlrev_b64 v[60:61], 12, v[84:85]
	v_lshl_add_u64 v[60:61], s[74:75], 0, v[60:61]
	v_lshlrev_b64 v[82:83], 11, v[84:85]
	v_cndmask_b32_e32 v85, 0, v103, vcc
	v_cndmask_b32_e32 v84, v98, v102, vcc
	v_lshl_add_u64 v[60:61], v[60:61], 0, s[14:15]
	v_cndmask_b32_e32 v99, v1, v86, vcc
	v_cndmask_b32_e32 v98, v87, v88, vcc
	v_lshl_add_u64 v[82:83], s[10:11], 0, v[82:83]
	v_lshlrev_b64 v[84:85], 12, v[84:85]
	v_lshl_add_u64 v[60:61], v[60:61], 0, v[66:67]
	v_lshl_add_u64 v[84:85], v[98:99], 0, v[84:85]
	v_lshl_add_u64 v[82:83], v[82:83], 0, s[16:17]
	v_lshl_add_u64 v[84:85], v[84:85], 0, s[14:15]
	v_lshl_add_u64 v[82:83], v[82:83], 0, v[62:63]
	v_lshl_add_u64 v[84:85], v[84:85], 0, v[66:67]
	v_cmp_lt_i32_e32 vcc, v92, v90
	v_mad_u64_u32 v[98:99], s[4:5], v59, s40, v[66:67]
	v_cmp_eq_u32_e64 s[4:5], 0, v110
	s_waitcnt vmcnt(28) lgkmcnt(0)
	v_pk_fma_f32 v[74:75], v[2:3], v[78:79], v[168:169]
	v_pk_fma_f32 v[76:77], v[4:5], v[80:81], v[170:171]
	global_store_dwordx4 v[60:61], v[74:77], off
	v_pk_mul_f32 v[60:61], v[64:65], v[74:75]
	v_pk_mul_f32 v[78:79], v[70:71], v[76:77]
	v_cvt_pk_bf16_f32 v60, v60, v61
	v_cvt_pk_bf16_f32 v61, v78, v79
	global_store_dwordx2 v[82:83], v[60:61], off
	v_cndmask_b32_e32 v60, v89, v92, vcc
	v_cmp_lt_i32_e32 vcc, v93, v90
	v_lshlrev_b32_e32 v115, 2, v60
	v_add_u32_e32 v60, s12, v59
	v_cndmask_b32_e32 v61, v89, v93, vcc
	v_cmp_lt_i32_e32 vcc, v94, v90
	v_add_u32_e32 v59, 0xffffe000, v60
	v_lshlrev_b32_e32 v116, 2, v61
	v_cndmask_b32_e32 v82, v89, v94, vcc
	v_cmp_lt_i32_e32 vcc, v95, v90
	v_ashrrev_i32_e32 v61, 31, v60
	v_lshlrev_b32_e32 v117, 2, v82
	v_cndmask_b32_e32 v83, v89, v95, vcc
	v_cmp_lt_i32_e32 vcc, v96, v90
	v_lshlrev_b32_e32 v118, 2, v83
	ds_read_b128 v[82:85], v72 offset:14560
	ds_read_b128 v[98:101], v98
	v_cndmask_b32_e32 v113, v89, v96, vcc
	v_cmp_gt_i32_e32 vcc, s41, v60
	v_lshlrev_b64 v[72:73], 12, v[102:103]
	v_lshlrev_b64 v[102:103], 11, v[102:103]
	v_cndmask_b32_e32 v104, v59, v60, vcc
	v_add_f32_e32 v59, v6, v9
	v_pk_mul_f32 v[6:7], v[10:11], v[10:11]
	v_cndmask_b32_e32 v105, 0, v61, vcc
	v_pk_mul_f32 v[8:9], v[12:13], v[12:13]
	v_add_f32_e32 v6, v6, v7
	v_cndmask_b32_e32 v107, v1, v86, vcc
	v_cndmask_b32_e32 v106, v87, v88, vcc
	v_lshlrev_b64 v[104:105], 12, v[104:105]
	v_add_f32_e32 v6, v6, v8
	v_lshl_add_u64 v[104:105], v[106:107], 0, v[104:105]
	v_add_f32_e32 v106, v6, v9
	v_pk_mul_f32 v[6:7], v[14:15], v[14:15]
	v_pk_mul_f32 v[8:9], v[16:17], v[16:17]
	v_add_f32_e32 v6, v6, v7
	v_add_f32_e32 v6, v6, v8
	v_add_f32_e32 v107, v6, v9
	v_pk_mul_f32 v[6:7], v[18:19], v[18:19]
	v_pk_mul_f32 v[8:9], v[20:21], v[20:21]
	v_add_f32_e32 v6, v6, v7
	v_add_f32_e32 v6, v6, v8
	v_add_f32_e32 v20, v6, v9
	v_pk_mul_f32 v[6:7], v[22:23], v[22:23]
	v_pk_mul_f32 v[8:9], v[24:25], v[24:25]
	v_add_f32_e32 v6, v6, v7
	v_add_f32_e32 v6, v6, v8
	v_add_f32_e32 v21, v6, v9
	v_pk_mul_f32 v[6:7], v[26:27], v[26:27]
	v_pk_mul_f32 v[8:9], v[28:29], v[28:29]
	v_add_f32_e32 v6, v6, v7
	v_add_f32_e32 v6, v6, v8
	v_add_f32_e32 v22, v6, v9
	v_pk_mul_f32 v[6:7], v[30:31], v[30:31]
	v_pk_mul_f32 v[8:9], v[32:33], v[32:33]
	v_add_f32_e32 v6, v6, v7
	v_add_f32_e32 v6, v6, v8
	v_lshl_add_u64 v[72:73], s[74:75], 0, v[72:73]
	v_lshl_add_u64 v[102:103], s[10:11], 0, v[102:103]
	v_add_f32_e32 v23, v6, v9
	v_lshl_add_u64 v[72:73], v[72:73], 0, s[14:15]
	v_lshl_add_u64 v[102:103], v[102:103], 0, s[16:17]
	v_lshl_add_u64 v[104:105], v[104:105], 0, s[14:15]
	v_lshl_add_u64 v[72:73], v[72:73], 0, v[66:67]
	v_lshl_add_u64 v[102:103], v[102:103], 0, v[62:63]
	v_lshl_add_u64 v[104:105], v[104:105], 0, v[66:67]
	v_pk_mul_f32 v[14:15], v[34:35], v[34:35]
	v_pk_mul_f32 v[16:17], v[36:37], v[36:37]
	v_add_f32_e32 v14, v14, v15
	v_add_f32_e32 v14, v14, v16
	v_add_f32_e32 v24, v14, v17
	v_pk_mul_f32 v[14:15], v[38:39], v[38:39]
	v_pk_mul_f32 v[16:17], v[40:41], v[40:41]
	v_add_f32_e32 v14, v14, v15
	v_add_f32_e32 v14, v14, v16
	v_add_f32_e32 v14, v14, v17
	v_cmp_eq_u32_e32 vcc, 0, v97
	v_pk_mul_f32 v[16:17], v[44:45], v[44:45]
	v_lshlrev_b64 v[108:109], 12, v[60:61]
	v_cndmask_b32_e32 v18, v14, v59, vcc
	s_waitcnt vmcnt(29) lgkmcnt(1)
	v_pk_fma_f32 v[6:7], v[2:3], v[82:83], v[172:173]
	v_pk_fma_f32 v[8:9], v[4:5], v[84:85], v[174:175]
	v_pk_mul_f32 v[10:11], v[64:65], v[6:7]
	v_pk_mul_f32 v[12:13], v[70:71], v[8:9]
	v_cvt_pk_bf16_f32 v10, v10, v11
	v_cvt_pk_bf16_f32 v11, v12, v13
	global_store_dwordx4 v[72:73], v[6:9], off
	global_store_dwordx2 v[102:103], v[10:11], off
	v_cndmask_b32_e32 v14, v59, v14, vcc
	ds_bpermute_b32 v19, v114, v14
	v_pk_mul_f32 v[14:15], v[42:43], v[42:43]
	v_pk_mul_f32 v[6:7], v[6:7], v[6:7]
	v_add_f32_e32 v14, v14, v15
	v_add_f32_e32 v14, v14, v16
	v_add_f32_e32 v25, v14, v17
	v_cndmask_b32_e32 v14, v106, v25, vcc
	ds_bpermute_b32 v26, v114, v14
	v_pk_mul_f32 v[14:15], v[46:47], v[46:47]
	v_pk_mul_f32 v[16:17], v[48:49], v[48:49]
	v_add_f32_e32 v14, v14, v15
	v_add_f32_e32 v14, v14, v16
	v_add_f32_e32 v14, v14, v17
	v_cndmask_b32_e32 v15, v107, v14, vcc
	ds_bpermute_b32 v15, v114, v15
	v_cndmask_b32_e32 v16, v25, v106, vcc
	v_cndmask_b32_e32 v14, v14, v107, vcc
	s_waitcnt lgkmcnt(1)
	v_add_f32_e32 v25, v16, v26
	v_pk_mul_f32 v[16:17], v[52:53], v[52:53]
	s_waitcnt lgkmcnt(0)
	v_add_f32_e32 v26, v14, v15
	v_pk_mul_f32 v[14:15], v[50:51], v[50:51]
	v_add_f32_e32 v27, v18, v19
	v_add_f32_e32 v14, v14, v15
	v_add_f32_e32 v16, v14, v16
	v_pk_mul_f32 v[14:15], v[54:55], v[54:55]
	v_pk_mul_f32 v[18:19], v[56:57], v[56:57]
	v_add_f32_e32 v14, v14, v15
	v_add_f32_e32 v14, v14, v18
	v_add_f32_e32 v14, v14, v19
	v_cndmask_b32_e32 v15, v21, v14, vcc
	ds_bpermute_b32 v15, v114, v15
	v_cndmask_b32_e32 v14, v14, v21, vcc
	v_add_f32_e32 v18, v16, v17
	v_cndmask_b32_e32 v16, v20, v18, vcc
	v_pk_mul_f32 v[8:9], v[8:9], v[8:9]
	s_waitcnt lgkmcnt(0)
	v_add_f32_e32 v14, v14, v15
	v_cndmask_b32_e64 v21, v14, v27, s[4:5]
	v_cndmask_b32_e64 v14, v27, v14, s[4:5]
	ds_bpermute_b32 v27, v115, v14
	v_pk_mul_f32 v[14:15], v[74:75], v[74:75]
	v_add_f32_e32 v6, v6, v7
	ds_bpermute_b32 v19, v114, v16
	v_pk_mul_f32 v[16:17], v[76:77], v[76:77]
	v_add_f32_e32 v14, v14, v15
	v_add_f32_e32 v6, v6, v8
	v_add_f32_e32 v14, v14, v16
	v_add_f32_e32 v6, v6, v9
	v_add_f32_e32 v14, v14, v17
	v_cndmask_b32_e32 v7, v23, v6, vcc
	v_cndmask_b32_e32 v15, v22, v14, vcc
	ds_bpermute_b32 v7, v114, v7
	ds_bpermute_b32 v15, v114, v15
	v_cndmask_b32_e32 v6, v6, v23, vcc
	v_cndmask_b32_e32 v16, v18, v20, vcc
	v_cndmask_b32_e32 v14, v14, v22, vcc
	s_waitcnt lgkmcnt(1)
	v_add_f32_e32 v18, v6, v7
	s_waitcnt lgkmcnt(0)
	v_add_f32_e32 v14, v14, v15
	v_cndmask_b32_e64 v6, v26, v18, s[4:5]
	v_add_f32_e32 v16, v16, v19
	v_cndmask_b32_e64 v8, v25, v14, s[4:5]
	ds_bpermute_b32 v19, v115, v6
	v_cndmask_b32_e64 v15, v14, v25, s[4:5]
	ds_bpermute_b32 v14, v115, v8
	v_add_f32_e32 v17, v21, v27
	v_lshl_add_u64 v[108:109], s[74:75], 0, v[108:109]
	v_lshlrev_b64 v[60:61], 11, v[60:61]
	s_waitcnt vmcnt(26)
	v_pk_fma_f32 v[2:3], v[2:3], v[98:99], v[120:121]
	v_pk_fma_f32 v[4:5], v[4:5], v[100:101], v[122:123]
	v_pk_mul_f32 v[6:7], v[2:3], v[2:3]
	v_pk_mul_f32 v[8:9], v[4:5], v[4:5]
	v_add_f32_e32 v6, v6, v7
	v_add_f32_e32 v6, v6, v8
	v_add_f32_e32 v6, v6, v9
	v_cndmask_b32_e32 v7, v24, v6, vcc
	ds_bpermute_b32 v7, v114, v7
	v_cndmask_b32_e32 v6, v6, v24, vcc
	v_cndmask_b32_e64 v8, v18, v26, s[4:5]
	s_waitcnt lgkmcnt(1)
	v_add_f32_e32 v10, v15, v14
	v_add_f32_e32 v8, v8, v19
	s_waitcnt lgkmcnt(0)
	v_add_f32_e32 v6, v6, v7
	v_cndmask_b32_e64 v7, v16, v6, s[4:5]
	ds_bpermute_b32 v7, v115, v7
	v_cndmask_b32_e64 v6, v6, v16, s[4:5]
	v_cmp_eq_u32_e32 vcc, 0, v111
	s_waitcnt lgkmcnt(0)
	v_add_f32_e32 v13, v6, v7
	v_cndmask_b32_e32 v11, v8, v17, vcc
	v_cndmask_b32_e32 v8, v17, v8, vcc
	v_cndmask_b32_e32 v6, v10, v13, vcc
	ds_bpermute_b32 v12, v116, v8
	ds_bpermute_b32 v14, v116, v6
	v_cndmask_b32_e32 v10, v13, v10, vcc
	v_cmp_eq_u32_e32 vcc, 0, v112
	v_lshl_add_u64 v[8:9], v[108:109], 0, s[14:15]
	s_waitcnt lgkmcnt(1)
	v_add_f32_e32 v11, v11, v12
	s_waitcnt lgkmcnt(0)
	v_add_f32_e32 v10, v10, v14
	v_cndmask_b32_e32 v12, v11, v10, vcc
	ds_bpermute_b32 v12, v117, v12
	v_lshl_add_u64 v[8:9], v[8:9], 0, v[66:67]
	global_store_dwordx4 v[8:9], v[2:5], off
	v_cndmask_b32_e32 v8, v10, v11, vcc
	v_lshl_add_u64 v[6:7], s[10:11], 0, v[60:61]
	s_waitcnt lgkmcnt(0)
	v_add_f32_e32 v10, v8, v12
	ds_bpermute_b32 v11, v118, v10
	v_pk_mul_f32 v[2:3], v[64:65], v[2:3]
	v_lshl_add_u64 v[6:7], v[6:7], 0, s[16:17]
	v_cvt_pk_bf16_f32 v8, v2, v3
	v_lshlrev_b32_e32 v3, 2, v113
	s_waitcnt lgkmcnt(0)
	v_add_f32_e32 v2, v10, v11
	ds_bpermute_b32 v3, v3, v2
	v_pk_mul_f32 v[4:5], v[70:71], v[4:5]
	s_nop 0
	v_cvt_pk_bf16_f32 v9, v4, v5
	v_lshl_add_u64 v[4:5], v[6:7], 0, v[62:63]
	global_store_dwordx2 v[4:5], v[8:9], off
	v_and_b32_e32 v4, 3, v69
	v_cmp_eq_u32_e32 vcc, 0, v4
	s_and_saveexec_b64 s[4:5], vcc
	s_cbranch_execz .LBB0_625
	s_lshl_b64 s[12:13], s[12:13], 2
	s_add_u32 s12, s23, s12
	s_addc_u32 s13, s24, s13
	v_ashrrev_i32_e32 v59, 31, v58
	s_waitcnt lgkmcnt(0)
	v_add_f32_e32 v4, v2, v3
	v_lshl_add_u64 v[2:3], v[58:59], 2, s[12:13]
	v_mov_b32_e32 v69, v67
	v_lshl_add_u64 v[2:3], v[2:3], 0, v[68:69]
	global_atomic_add_f32 v[2:3], v4, off
	s_branch .LBB0_625

	.amdhsa_kernel _Z4mega1P
		.amdhsa_group_segment_fixed_size 147472
		.amdhsa_private_segment_fixed_size 0
		.amdhsa_kernarg_size 488
		.amdhsa_user_sgpr_count 2
		.amdhsa_user_sgpr_dispatch_ptr 0
		.amdhsa_user_sgpr_queue_ptr 0
		.amdhsa_user_sgpr_kernarg_segment_ptr 1
		.amdhsa_user_sgpr_dispatch_id 0
		.amdhsa_user_sgpr_kernarg_preload_length 0
		.amdhsa_user_sgpr_kernarg_preload_offset 0
		.amdhsa_user_sgpr_private_segment_size 0
		.amdhsa_uses_dynamic_stack 0
		.amdhsa_enable_private_segment 0
		.amdhsa_system_sgpr_workgroup_id_x 1
		.amdhsa_system_sgpr_workgroup_id_y 0
		.amdhsa_system_sgpr_workgroup_id_z 0
		.amdhsa_system_sgpr_workgroup_info 0
		.amdhsa_system_vgpr_workitem_id 2
		.amdhsa_next_free_vgpr 248
		.amdhsa_next_free_sgpr 100
		.amdhsa_accum_offset 248
		.amdhsa_reserve_vcc 1
		.amdhsa_float_round_mode_32 0
		.amdhsa_float_round_mode_16_64 0
		.amdhsa_float_denorm_mode_32 3
		.amdhsa_float_denorm_mode_16_64 3
		.amdhsa_dx10_clamp 1
		.amdhsa_ieee_mode 1
		.amdhsa_fp16_overflow 0
		.amdhsa_tg_split 0
		.amdhsa_exception_fp_ieee_invalid_op 0
		.amdhsa_exception_fp_denorm_src 0
		.amdhsa_exception_fp_ieee_div_zero 0
		.amdhsa_exception_fp_ieee_overflow 0
		.amdhsa_exception_fp_ieee_underflow 0
		.amdhsa_exception_fp_ieee_inexact 0
		.amdhsa_exception_int_div_zero 0
	.end_amdhsa_kernel

amdhsa.kernels:
  - .agpr_count:     0
    .args:
      - .offset:         0
        .size:           232
        .value_kind:     by_value
      - .offset:         232
        .size:           4
        .value_kind:     hidden_block_count_x
      - .offset:         236
        .size:           4
        .value_kind:     hidden_block_count_y
      - .offset:         240
        .size:           4
        .value_kind:     hidden_block_count_z
      - .offset:         244
        .size:           2
        .value_kind:     hidden_group_size_x
      - .offset:         246
        .size:           2
        .value_kind:     hidden_group_size_y
      - .offset:         248
        .size:           2
        .value_kind:     hidden_group_size_z
      - .offset:         250
        .size:           2
        .value_kind:     hidden_remainder_x
      - .offset:         252
        .size:           2
        .value_kind:     hidden_remainder_y
      - .offset:         254
        .size:           2
        .value_kind:     hidden_remainder_z
      - .offset:         272
        .size:           8
        .value_kind:     hidden_global_offset_x
      - .offset:         280
        .size:           8
        .value_kind:     hidden_global_offset_y
      - .offset:         288
        .size:           8
        .value_kind:     hidden_global_offset_z
      - .offset:         296
        .size:           2
        .value_kind:     hidden_grid_dims
      - .offset:         320
        .size:           8
        .value_kind:     hidden_multigrid_sync_arg
    .group_segment_fixed_size: 147472
    .kernarg_segment_align: 8
    .kernarg_segment_size: 488
    .language:       OpenCL C
    .language_version:
      - 2
      - 0
    .max_flat_workgroup_size: 512
    .name:           _Z4mega1P
    .private_segment_fixed_size: 0
    .sgpr_count:     106
    .sgpr_spill_count: 74
    .symbol:         _Z4mega1P.kd
    .uniform_work_group_size: 1
    .uses_dynamic_stack: false
    .vgpr_count:     248
    .vgpr_spill_count: 0
    .wavefront_size: 64
